# GEMM main loops: all per-phase s_setprio flips removed
# speedup vs baseline: 1.0544x; 1.0058x over previous
; #define STAGE(bufoff, gbase, voff) do { _Pragma("unroll") for (int _i = 0; _i < 2; ++_i) \
;     __builtin_amdgcn_global_load_lds((const unsigned*)((const char*)(gbase) + (voff)[_i]), (LAS unsigned*)(lds + (bufoff) + ldsw + _i * 8192), 16, 0, 0); } while (0)
; #define LDA(dst, b, h) do { _Pragma("unroll") for (int m = 0; m < 4; ++m) _Pragma("unroll") for (int k = 0; k < 2; ++k) dst[m][k] = *(const LAS half8*)(lds + SA(b, h) + aoff + m * 2048 + k * 1024); } while (0)
; #define LDB(dst, b, h) do { _Pragma("unroll") for (int n = 0; n < 2; ++n) _Pragma("unroll") for (int k = 0; k < 2; ++k) dst[n][k] = *(const LAS half8*)(lds + SB(b, h) + boff + n * 2048 + k * 1024); } while (0)
; #define MMA(ai, bj, At_, Bt_) do { __builtin_amdgcn_s_setprio(1); \
;     _Pragma("unroll") for (int m = 0; m < 4; ++m) _Pragma("unroll") for (int n = 0; n < 2; ++n) _Pragma("unroll") for (int k = 0; k < 2; ++k) \
;       acc[ai][bj][m][n] = MFMA16(Bt_[n][k], At_[m][k], acc[ai][bj][m][n]); \
;     __builtin_amdgcn_s_setprio(0); } while (0)
; #define WAIT_V(n) asm volatile("s_waitcnt vmcnt(" #n ")" ::: "memory")
; #define WAIT_L(n) asm volatile("s_waitcnt lgkmcnt(" #n ")" ::: "memory")
; #define BAR __builtin_amdgcn_s_barrier()
; #define SCHED __builtin_amdgcn_sched_barrier(0)
; template <int EPI>
; DI void gemm_phase(const int wid_s, const h16* __restrict__ A, const h16* __restrict__ Bt, const int N, const int K, const EpiArgs ea) {
;     ...
;       const char* a1 = cA + (size_t)(t + 1) * kstep;
;       const char* a2 = last ? nA : cA + (size_t)(t + 2) * kstep; const char* b2 = last ? nB : cB + (size_t)(t + 2) * kstep;
;       const char* a3 = a2 + kstep; const char* b3 = b2 + kstep;
;       LDB(B0, 0, 0); LDB(B1, 0, 1); SCHED; LDA(At, 0, 0); STAGE(SA(1, 1), a1 + hstep, voffA);
;       WAIT_V(8); WAIT_L(0); BAR; MMA(0, 0, At, B0); MMA(0, 1, At, B1); BAR; SCHED;
;       LDA(At, 0, 1); STAGE(SB(0, 0), b2, voffB); STAGE(SB(0, 1), b2 + hstep, voffB); STAGE(SA(0, 0), a2, voffA);
;       WAIT_V(8); WAIT_L(0); BAR; MMA(1, 0, At, B0); MMA(1, 1, At, B1); BAR; SCHED;
.LBB0_122:
	s_add_u32 s14, s12, 0x100
	s_addc_u32 s15, s13, 0
	s_add_i32 s46, 0, 0x10000
	s_cmp_eq_u32 s45, 40
	s_cselect_b32 s19, s9, s15
	s_cselect_b32 s18, s8, s14
	v_add_u32_e32 v177, s46, v148
	s_cselect_b32 s17, s42, s44
	s_cselect_b32 s16, s41, s43
	s_add_i32 s47, 0, 0x14000
	ds_read_b128 v[144:147], v177
	ds_read_b128 v[152:155], v177 offset:1024
	ds_read_b128 v[178:181], v177 offset:2048
	ds_read_b128 v[182:185], v177 offset:3072
	v_add_u32_e32 v177, s47, v148
	ds_read_b128 v[186:189], v177
	ds_read_b128 v[190:193], v177 offset:1024
	ds_read_b128 v[194:197], v177 offset:2048
	ds_read_b128 v[198:201], v177 offset:3072
	v_lshl_add_u64 v[234:235], s[12:13], 0, v[142:143]
	s_add_i32 m0, s22, 0xc000
	ds_read_b128 v[202:205], v151
	ds_read_b128 v[206:209], v151 offset:1024
	ds_read_b128 v[210:213], v151 offset:2048
	ds_read_b128 v[214:217], v151 offset:3072
	ds_read_b128 v[218:221], v151 offset:4096
	ds_read_b128 v[222:225], v151 offset:5120
	ds_read_b128 v[226:229], v151 offset:6144
	ds_read_b128 v[230:233], v151 offset:7168
	global_load_lds_dwordx4 v[234:235], off
	v_lshl_add_u64 v[234:235], s[12:13], 0, v[140:141]
	s_add_i32 m0, s22, 0xe000
	s_nop 0
	global_load_lds_dwordx4 v[234:235], off
	s_waitcnt vmcnt(8)
	s_waitcnt lgkmcnt(0)
	s_barrier
	s_waitcnt lgkmcnt(0)
	v_mfma_f32_16x16x32_f16 v[130:133], v[144:147], v[202:205], v[130:133]
	v_mfma_f32_16x16x32_f16 v[126:129], v[178:181], v[202:205], v[126:129]
	v_mfma_f32_16x16x32_f16 v[114:117], v[144:147], v[210:213], v[114:117]
	v_mfma_f32_16x16x32_f16 v[110:113], v[178:181], v[210:213], v[110:113]
	v_mfma_f32_16x16x32_f16 v[98:101], v[144:147], v[218:221], v[98:101]
	v_mfma_f32_16x16x32_f16 v[94:97], v[178:181], v[218:221], v[94:97]
	v_mfma_f32_16x16x32_f16 v[82:85], v[144:147], v[226:229], v[82:85]
	v_mfma_f32_16x16x32_f16 v[78:81], v[178:181], v[226:229], v[78:81]
	v_mfma_f32_16x16x32_f16 v[130:133], v[152:155], v[206:209], v[130:133]
	v_mfma_f32_16x16x32_f16 v[126:129], v[182:185], v[206:209], v[126:129]
	v_mfma_f32_16x16x32_f16 v[114:117], v[152:155], v[214:217], v[114:117]
	v_mfma_f32_16x16x32_f16 v[110:113], v[182:185], v[214:217], v[110:113]
	v_mfma_f32_16x16x32_f16 v[98:101], v[152:155], v[222:225], v[98:101]
	v_mfma_f32_16x16x32_f16 v[94:97], v[182:185], v[222:225], v[94:97]
	v_mfma_f32_16x16x32_f16 v[82:85], v[152:155], v[230:233], v[82:85]
	v_mfma_f32_16x16x32_f16 v[78:81], v[182:185], v[230:233], v[78:81]
	v_mfma_f32_16x16x32_f16 v[122:125], v[186:189], v[202:205], v[122:125]
	v_mfma_f32_16x16x32_f16 v[118:121], v[194:197], v[202:205], v[118:121]
	v_mfma_f32_16x16x32_f16 v[106:109], v[186:189], v[210:213], v[106:109]
	v_mfma_f32_16x16x32_f16 v[102:105], v[194:197], v[210:213], v[102:105]
	v_mfma_f32_16x16x32_f16 v[90:93], v[186:189], v[218:221], v[90:93]
	v_mfma_f32_16x16x32_f16 v[86:89], v[194:197], v[218:221], v[86:89]
	v_mfma_f32_16x16x32_f16 v[74:77], v[186:189], v[226:229], v[74:77]
	v_mfma_f32_16x16x32_f16 v[70:73], v[194:197], v[226:229], v[70:73]
	v_mfma_f32_16x16x32_f16 v[122:125], v[190:193], v[206:209], v[122:125]
	v_mfma_f32_16x16x32_f16 v[118:121], v[198:201], v[206:209], v[118:121]
	v_mfma_f32_16x16x32_f16 v[106:109], v[190:193], v[214:217], v[106:109]
	v_mfma_f32_16x16x32_f16 v[102:105], v[198:201], v[214:217], v[102:105]
	v_mfma_f32_16x16x32_f16 v[90:93], v[190:193], v[222:225], v[90:93]
	v_mfma_f32_16x16x32_f16 v[86:89], v[198:201], v[222:225], v[86:89]
	v_mfma_f32_16x16x32_f16 v[74:77], v[190:193], v[230:233], v[74:77]
	v_mfma_f32_16x16x32_f16 v[70:73], v[198:201], v[230:233], v[70:73]
	s_barrier
	s_add_i32 s12, s46, s21
	v_lshl_add_u64 v[234:235], s[16:17], 0, v[0:1]
	s_mov_b32 m0, s12
	ds_read_b128 v[202:205], v151 offset:16384
	ds_read_b128 v[206:209], v151 offset:17408
	ds_read_b128 v[210:213], v151 offset:18432
	ds_read_b128 v[214:217], v151 offset:19456
	ds_read_b128 v[218:221], v151 offset:20480
	ds_read_b128 v[222:225], v151 offset:21504
	ds_read_b128 v[226:229], v151 offset:22528
	ds_read_b128 v[230:233], v151 offset:23552
	global_load_lds_dwordx4 v[234:235], off
	s_add_i32 m0, s12, 0x2000
	s_add_u32 s12, s16, 0xb0000
	v_lshl_add_u64 v[236:237], s[16:17], 0, v[138:139]
	s_addc_u32 s13, s17, 0
	s_add_i32 s46, s47, s21
	global_load_lds_dwordx4 v[236:237], off
	v_lshl_add_u64 v[238:239], s[12:13], 0, v[0:1]
	s_mov_b32 m0, s46
	v_lshl_add_u64 v[240:241], s[18:19], 0, v[134:135]
	global_load_lds_dwordx4 v[238:239], off
	v_lshl_add_u64 v[238:239], s[12:13], 0, v[138:139]
	s_add_i32 m0, s46, 0x2000
	s_nop 0
	global_load_lds_dwordx4 v[238:239], off
	v_lshl_add_u64 v[238:239], s[18:19], 0, v[2:3]
	s_mov_b32 m0, s22
	s_nop 0
	global_load_lds_dwordx4 v[238:239], off
	s_mov_b32 m0, s23
	s_nop 0
	global_load_lds_dwordx4 v[240:241], off
	s_waitcnt vmcnt(8)
	s_waitcnt lgkmcnt(0)
	s_barrier
; #define STAGE(bufoff, gbase, voff) do { _Pragma("unroll") for (int _i = 0; _i < 2; ++_i) \
;     __builtin_amdgcn_global_load_lds((const unsigned*)((const char*)(gbase) + (voff)[_i]), (LAS unsigned*)(lds + (bufoff) + ldsw + _i * 8192), 16, 0, 0); } while (0)
; #define LDA(dst, b, h) do { _Pragma("unroll") for (int m = 0; m < 4; ++m) _Pragma("unroll") for (int k = 0; k < 2; ++k) dst[m][k] = *(const LAS half8*)(lds + SA(b, h) + aoff + m * 2048 + k * 1024); } while (0)
; #define LDB(dst, b, h) do { _Pragma("unroll") for (int n = 0; n < 2; ++n) _Pragma("unroll") for (int k = 0; k < 2; ++k) dst[n][k] = *(const LAS half8*)(lds + SB(b, h) + boff + n * 2048 + k * 1024); } while (0)
; #define MMA(ai, bj, At_, Bt_) do { __builtin_amdgcn_s_setprio(1); \
;     _Pragma("unroll") for (int m = 0; m < 4; ++m) _Pragma("unroll") for (int n = 0; n < 2; ++n) _Pragma("unroll") for (int k = 0; k < 2; ++k) \
;       acc[ai][bj][m][n] = MFMA16(Bt_[n][k], At_[m][k], acc[ai][bj][m][n]); \
;     __builtin_amdgcn_s_setprio(0); } while (0)
; #define WAIT_V(n) asm volatile("s_waitcnt vmcnt(" #n ")" ::: "memory")
; #define WAIT_L(n) asm volatile("s_waitcnt lgkmcnt(" #n ")" ::: "memory")
; #define BAR __builtin_amdgcn_s_barrier()
; #define SCHED __builtin_amdgcn_sched_barrier(0)
; template <int EPI>
; DI void gemm_phase(const int wid_s, const h16* __restrict__ A, const h16* __restrict__ Bt, const int N, const int K, const EpiArgs ea) {
;     ...
;       WAIT_V(8); WAIT_L(0); BAR; MMA(1, 0, At, B0); MMA(1, 1, At, B1); BAR; SCHED;
;       LDB(B0, 1, 0); LDB(B1, 1, 1); SCHED; LDA(At, 1, 0); STAGE(SA(0, 1), a2 + hstep, voffA);
;       WAIT_V(8); WAIT_L(0); BAR; MMA(0, 0, At, B0); MMA(0, 1, At, B1); BAR; SCHED;
	s_waitcnt lgkmcnt(0)
	v_mfma_f32_16x16x32_f16 v[66:69], v[144:147], v[202:205], v[66:69]
	v_mfma_f32_16x16x32_f16 v[62:65], v[178:181], v[202:205], v[62:65]
	v_mfma_f32_16x16x32_f16 v[50:53], v[144:147], v[210:213], v[50:53]
	v_mfma_f32_16x16x32_f16 v[46:49], v[178:181], v[210:213], v[46:49]
	v_mfma_f32_16x16x32_f16 v[34:37], v[144:147], v[218:221], v[34:37]
	v_mfma_f32_16x16x32_f16 v[30:33], v[178:181], v[218:221], v[30:33]
	v_mfma_f32_16x16x32_f16 v[18:21], v[144:147], v[226:229], v[18:21]
	v_mfma_f32_16x16x32_f16 v[14:17], v[178:181], v[226:229], v[14:17]
	v_mfma_f32_16x16x32_f16 v[66:69], v[152:155], v[206:209], v[66:69]
	v_mfma_f32_16x16x32_f16 v[62:65], v[182:185], v[206:209], v[62:65]
	v_mfma_f32_16x16x32_f16 v[50:53], v[152:155], v[214:217], v[50:53]
	v_mfma_f32_16x16x32_f16 v[46:49], v[182:185], v[214:217], v[46:49]
	v_mfma_f32_16x16x32_f16 v[34:37], v[152:155], v[222:225], v[34:37]
	v_mfma_f32_16x16x32_f16 v[30:33], v[182:185], v[222:225], v[30:33]
	v_mfma_f32_16x16x32_f16 v[18:21], v[152:155], v[230:233], v[18:21]
	v_mfma_f32_16x16x32_f16 v[14:17], v[182:185], v[230:233], v[14:17]
	v_mfma_f32_16x16x32_f16 v[58:61], v[186:189], v[202:205], v[58:61]
	v_mfma_f32_16x16x32_f16 v[54:57], v[194:197], v[202:205], v[54:57]
	v_mfma_f32_16x16x32_f16 v[42:45], v[186:189], v[210:213], v[42:45]
	v_mfma_f32_16x16x32_f16 v[38:41], v[194:197], v[210:213], v[38:41]
	v_mfma_f32_16x16x32_f16 v[26:29], v[186:189], v[218:221], v[26:29]
	v_mfma_f32_16x16x32_f16 v[22:25], v[194:197], v[218:221], v[22:25]
	v_mfma_f32_16x16x32_f16 v[10:13], v[186:189], v[226:229], v[10:13]
	v_mfma_f32_16x16x32_f16 v[6:9], v[194:197], v[226:229], v[6:9]
	v_mfma_f32_16x16x32_f16 v[58:61], v[190:193], v[206:209], v[58:61]
	v_mfma_f32_16x16x32_f16 v[54:57], v[198:201], v[206:209], v[54:57]
	v_mfma_f32_16x16x32_f16 v[42:45], v[190:193], v[214:217], v[42:45]
	v_mfma_f32_16x16x32_f16 v[38:41], v[198:201], v[214:217], v[38:41]
	v_mfma_f32_16x16x32_f16 v[26:29], v[190:193], v[222:225], v[26:29]
	v_mfma_f32_16x16x32_f16 v[22:25], v[198:201], v[222:225], v[22:25]
	v_mfma_f32_16x16x32_f16 v[10:13], v[190:193], v[230:233], v[10:13]
	v_mfma_f32_16x16x32_f16 v[6:9], v[198:201], v[230:233], v[6:9]
	s_barrier
	s_add_i32 s46, 0, 0x18000
	v_add_u32_e32 v177, s46, v148
	s_add_i32 s47, 0, 0x1c000
	ds_read_b128 v[144:147], v177
	ds_read_b128 v[152:155], v177 offset:1024
	ds_read_b128 v[178:181], v177 offset:2048
	ds_read_b128 v[182:185], v177 offset:3072
	v_add_u32_e32 v177, s47, v148
	ds_read_b128 v[186:189], v177
	ds_read_b128 v[190:193], v177 offset:1024
	ds_read_b128 v[194:197], v177 offset:2048
	ds_read_b128 v[198:201], v177 offset:3072
	s_add_u32 s12, s18, 0xb0000
	s_addc_u32 s13, s19, 0
	s_mov_b32 m0, s24
	v_lshl_add_u64 v[242:243], s[12:13], 0, v[2:3]
	ds_read_b128 v[202:205], v151 offset:32768
	ds_read_b128 v[206:209], v151 offset:33792
	ds_read_b128 v[210:213], v151 offset:34816
	ds_read_b128 v[214:217], v151 offset:35840
	ds_read_b128 v[218:221], v151 offset:36864
	ds_read_b128 v[222:225], v151 offset:37888
	ds_read_b128 v[226:229], v151 offset:38912
	ds_read_b128 v[230:233], v151 offset:39936
	global_load_lds_dwordx4 v[242:243], off
	v_lshl_add_u64 v[242:243], s[12:13], 0, v[134:135]
	s_mov_b32 m0, s26
	s_nop 0
	global_load_lds_dwordx4 v[242:243], off
	s_waitcnt vmcnt(8)
	s_waitcnt lgkmcnt(0)
	s_barrier
	s_waitcnt lgkmcnt(0)
	v_mfma_f32_16x16x32_f16 v[130:133], v[144:147], v[202:205], v[130:133]
	v_mfma_f32_16x16x32_f16 v[126:129], v[178:181], v[202:205], v[126:129]
	v_mfma_f32_16x16x32_f16 v[114:117], v[144:147], v[210:213], v[114:117]
	v_mfma_f32_16x16x32_f16 v[110:113], v[178:181], v[210:213], v[110:113]
	v_mfma_f32_16x16x32_f16 v[98:101], v[144:147], v[218:221], v[98:101]
	v_mfma_f32_16x16x32_f16 v[94:97], v[178:181], v[218:221], v[94:97]
	v_mfma_f32_16x16x32_f16 v[82:85], v[144:147], v[226:229], v[82:85]
	v_mfma_f32_16x16x32_f16 v[78:81], v[178:181], v[226:229], v[78:81]
	v_mfma_f32_16x16x32_f16 v[130:133], v[152:155], v[206:209], v[130:133]
	v_mfma_f32_16x16x32_f16 v[126:129], v[182:185], v[206:209], v[126:129]
	v_mfma_f32_16x16x32_f16 v[114:117], v[152:155], v[214:217], v[114:117]
	v_mfma_f32_16x16x32_f16 v[110:113], v[182:185], v[214:217], v[110:113]
	v_mfma_f32_16x16x32_f16 v[98:101], v[152:155], v[222:225], v[98:101]
	v_mfma_f32_16x16x32_f16 v[94:97], v[182:185], v[222:225], v[94:97]
	v_mfma_f32_16x16x32_f16 v[82:85], v[152:155], v[230:233], v[82:85]
	v_mfma_f32_16x16x32_f16 v[78:81], v[182:185], v[230:233], v[78:81]
	v_mfma_f32_16x16x32_f16 v[122:125], v[186:189], v[202:205], v[122:125]
	v_mfma_f32_16x16x32_f16 v[118:121], v[194:197], v[202:205], v[118:121]
	v_mfma_f32_16x16x32_f16 v[106:109], v[186:189], v[210:213], v[106:109]
	v_mfma_f32_16x16x32_f16 v[102:105], v[194:197], v[210:213], v[102:105]
	v_mfma_f32_16x16x32_f16 v[90:93], v[186:189], v[218:221], v[90:93]
	v_mfma_f32_16x16x32_f16 v[86:89], v[194:197], v[218:221], v[86:89]
	v_mfma_f32_16x16x32_f16 v[74:77], v[186:189], v[226:229], v[74:77]
	v_mfma_f32_16x16x32_f16 v[70:73], v[194:197], v[226:229], v[70:73]
	v_mfma_f32_16x16x32_f16 v[122:125], v[190:193], v[206:209], v[122:125]
	v_mfma_f32_16x16x32_f16 v[118:121], v[198:201], v[206:209], v[118:121]
	v_mfma_f32_16x16x32_f16 v[106:109], v[190:193], v[214:217], v[106:109]
	v_mfma_f32_16x16x32_f16 v[102:105], v[198:201], v[214:217], v[102:105]
	v_mfma_f32_16x16x32_f16 v[90:93], v[190:193], v[222:225], v[90:93]
	v_mfma_f32_16x16x32_f16 v[86:89], v[198:201], v[222:225], v[86:89]
	v_mfma_f32_16x16x32_f16 v[74:77], v[190:193], v[230:233], v[74:77]
	v_mfma_f32_16x16x32_f16 v[70:73], v[198:201], v[230:233], v[70:73]
	s_barrier
; #define STAGE(bufoff, gbase, voff) do { _Pragma("unroll") for (int _i = 0; _i < 2; ++_i) \
;     __builtin_amdgcn_global_load_lds((const unsigned*)((const char*)(gbase) + (voff)[_i]), (LAS unsigned*)(lds + (bufoff) + ldsw + _i * 8192), 16, 0, 0); } while (0)
; #define LDA(dst, b, h) do { _Pragma("unroll") for (int m = 0; m < 4; ++m) _Pragma("unroll") for (int k = 0; k < 2; ++k) dst[m][k] = *(const LAS half8*)(lds + SA(b, h) + aoff + m * 2048 + k * 1024); } while (0)
; #define MMA(ai, bj, At_, Bt_) do { __builtin_amdgcn_s_setprio(1); \
;     _Pragma("unroll") for (int m = 0; m < 4; ++m) _Pragma("unroll") for (int n = 0; n < 2; ++n) _Pragma("unroll") for (int k = 0; k < 2; ++k) \
;       acc[ai][bj][m][n] = MFMA16(Bt_[n][k], At_[m][k], acc[ai][bj][m][n]); \
;     __builtin_amdgcn_s_setprio(0); } while (0)
; #define WAIT_V(n) asm volatile("s_waitcnt vmcnt(" #n ")" ::: "memory")
; #define WAIT_L(n) asm volatile("s_waitcnt lgkmcnt(" #n ")" ::: "memory")
; #define BAR __builtin_amdgcn_s_barrier()
; #define SCHED __builtin_amdgcn_sched_barrier(0)
; template <int EPI>
; DI void gemm_phase(const int wid_s, const h16* __restrict__ A, const h16* __restrict__ Bt, const int N, const int K, const EpiArgs ea) {
;     ...
;     for (int t = 0; t < nt; t += 2) {
;     ...
;       LDA(At, 1, 1); STAGE(SB(1, 0), b3, voffB); STAGE(SB(1, 1), b3 + hstep, voffB); STAGE(SA(1, 0), a3, voffA);
;       WAIT_V(8); WAIT_L(0); BAR; MMA(1, 0, At, B0); MMA(1, 1, At, B1); BAR; SCHED;
;     }
	s_add_i32 s12, s46, s21
	v_lshl_add_u64 v[234:235], v[234:235], 0, s[36:37]
	s_mov_b32 m0, s12
	ds_read_b128 v[202:205], v151 offset:49152
	ds_read_b128 v[206:209], v151 offset:50176
	ds_read_b128 v[210:213], v151 offset:51200
	ds_read_b128 v[214:217], v151 offset:52224
	ds_read_b128 v[218:221], v151 offset:53248
	ds_read_b128 v[222:225], v151 offset:54272
	ds_read_b128 v[226:229], v151 offset:55296
	ds_read_b128 v[230:233], v151 offset:56320
	global_load_lds_dwordx4 v[234:235], off
	s_add_i32 m0, s12, 0x2000
	s_add_u32 s12, s16, 0xb0080
	v_lshl_add_u64 v[234:235], v[236:237], 0, s[36:37]
	s_addc_u32 s13, s17, 0
	s_add_i32 s16, s47, s21
	global_load_lds_dwordx4 v[234:235], off
	v_lshl_add_u64 v[234:235], s[12:13], 0, v[0:1]
	s_mov_b32 m0, s16
	s_nop 0
	global_load_lds_dwordx4 v[234:235], off
	v_lshl_add_u64 v[234:235], s[12:13], 0, v[138:139]
	s_add_i32 m0, s16, 0x2000
	s_nop 0
	global_load_lds_dwordx4 v[234:235], off
	v_lshl_add_u64 v[234:235], v[238:239], 0, s[36:37]
	s_mov_b32 m0, s27
	s_nop 0
	global_load_lds_dwordx4 v[234:235], off
	v_lshl_add_u64 v[234:235], v[240:241], 0, s[36:37]
	s_mov_b32 m0, s30
	s_nop 0
	global_load_lds_dwordx4 v[234:235], off
	s_waitcnt vmcnt(8)
	s_waitcnt lgkmcnt(0)
	s_barrier
	s_waitcnt lgkmcnt(0)
	v_mfma_f32_16x16x32_f16 v[66:69], v[144:147], v[202:205], v[66:69]
	v_mfma_f32_16x16x32_f16 v[62:65], v[178:181], v[202:205], v[62:65]
	v_mfma_f32_16x16x32_f16 v[50:53], v[144:147], v[210:213], v[50:53]
	v_mfma_f32_16x16x32_f16 v[46:49], v[178:181], v[210:213], v[46:49]
	v_mfma_f32_16x16x32_f16 v[34:37], v[144:147], v[218:221], v[34:37]
	v_mfma_f32_16x16x32_f16 v[30:33], v[178:181], v[218:221], v[30:33]
	v_mfma_f32_16x16x32_f16 v[18:21], v[144:147], v[226:229], v[18:21]
	v_mfma_f32_16x16x32_f16 v[14:17], v[178:181], v[226:229], v[14:17]
	v_mfma_f32_16x16x32_f16 v[66:69], v[152:155], v[206:209], v[66:69]
	v_mfma_f32_16x16x32_f16 v[62:65], v[182:185], v[206:209], v[62:65]
	v_mfma_f32_16x16x32_f16 v[50:53], v[152:155], v[214:217], v[50:53]
	v_mfma_f32_16x16x32_f16 v[46:49], v[182:185], v[214:217], v[46:49]
	v_mfma_f32_16x16x32_f16 v[34:37], v[152:155], v[222:225], v[34:37]
	v_mfma_f32_16x16x32_f16 v[30:33], v[182:185], v[222:225], v[30:33]
	v_mfma_f32_16x16x32_f16 v[18:21], v[152:155], v[230:233], v[18:21]
	v_mfma_f32_16x16x32_f16 v[14:17], v[182:185], v[230:233], v[14:17]
	v_mfma_f32_16x16x32_f16 v[58:61], v[186:189], v[202:205], v[58:61]
	v_mfma_f32_16x16x32_f16 v[54:57], v[194:197], v[202:205], v[54:57]
	v_mfma_f32_16x16x32_f16 v[42:45], v[186:189], v[210:213], v[42:45]
	v_mfma_f32_16x16x32_f16 v[38:41], v[194:197], v[210:213], v[38:41]
	v_mfma_f32_16x16x32_f16 v[26:29], v[186:189], v[218:221], v[26:29]
	v_mfma_f32_16x16x32_f16 v[22:25], v[194:197], v[218:221], v[22:25]
	v_mfma_f32_16x16x32_f16 v[10:13], v[186:189], v[226:229], v[10:13]
	v_mfma_f32_16x16x32_f16 v[6:9], v[194:197], v[226:229], v[6:9]
	v_mfma_f32_16x16x32_f16 v[58:61], v[190:193], v[206:209], v[58:61]
	v_mfma_f32_16x16x32_f16 v[54:57], v[198:201], v[206:209], v[54:57]
	v_mfma_f32_16x16x32_f16 v[42:45], v[190:193], v[214:217], v[42:45]
	v_mfma_f32_16x16x32_f16 v[38:41], v[198:201], v[214:217], v[38:41]
	v_mfma_f32_16x16x32_f16 v[26:29], v[190:193], v[222:225], v[26:29]
	v_mfma_f32_16x16x32_f16 v[22:25], v[198:201], v[222:225], v[22:25]
	v_mfma_f32_16x16x32_f16 v[10:13], v[190:193], v[230:233], v[10:13]
	v_mfma_f32_16x16x32_f16 v[6:9], v[198:201], v[230:233], v[6:9]
	s_barrier
	s_add_i32 s45, s45, 2
	s_add_u32 s43, s43, 0x100
	s_addc_u32 s44, s44, 0
	s_cmp_gt_u32 s45, 41
	s_mov_b64 s[12:13], s[14:15]
	s_cbranch_scc0 .LBB0_122
	s_and_b64 vcc, exec, s[4:5]
	s_cbranch_vccz .LBB0_125
	s_barrier

; #define STAGE(bufoff, gbase, voff) do { _Pragma("unroll") for (int _i = 0; _i < 2; ++_i) \
;     __builtin_amdgcn_global_load_lds((const unsigned*)((const char*)(gbase) + (voff)[_i]), (LAS unsigned*)(lds + (bufoff) + ldsw + _i * 8192), 16, 0, 0); } while (0)
; #define LDA(dst, b, h) do { _Pragma("unroll") for (int m = 0; m < 4; ++m) _Pragma("unroll") for (int k = 0; k < 2; ++k) dst[m][k] = *(const LAS half8*)(lds + SA(b, h) + aoff + m * 2048 + k * 1024); } while (0)
; #define LDB(dst, b, h) do { _Pragma("unroll") for (int n = 0; n < 2; ++n) _Pragma("unroll") for (int k = 0; k < 2; ++k) dst[n][k] = *(const LAS half8*)(lds + SB(b, h) + boff + n * 2048 + k * 1024); } while (0)
; #define MMA(ai, bj, At_, Bt_) do { __builtin_amdgcn_s_setprio(1); \
;     _Pragma("unroll") for (int m = 0; m < 4; ++m) _Pragma("unroll") for (int n = 0; n < 2; ++n) _Pragma("unroll") for (int k = 0; k < 2; ++k) \
;       acc[ai][bj][m][n] = MFMA16(Bt_[n][k], At_[m][k], acc[ai][bj][m][n]); \
;     __builtin_amdgcn_s_setprio(0); } while (0)
; #define WAIT_V(n) asm volatile("s_waitcnt vmcnt(" #n ")" ::: "memory")
; #define WAIT_L(n) asm volatile("s_waitcnt lgkmcnt(" #n ")" ::: "memory")
; #define BAR __builtin_amdgcn_s_barrier()
; #define SCHED __builtin_amdgcn_sched_barrier(0)
; template <int EPI>
; DI void gemm_phase(const int wid_s, const h16* __restrict__ A, const h16* __restrict__ Bt, const int N, const int K, const EpiArgs ea) {
;     ...
;       const char* a1 = cA + (size_t)(t + 1) * kstep;
;       const char* a2 = last ? nA : cA + (size_t)(t + 2) * kstep; const char* b2 = last ? nB : cB + (size_t)(t + 2) * kstep;
;       const char* a3 = a2 + kstep; const char* b3 = b2 + kstep;
;       LDB(B0, 0, 0); LDB(B1, 0, 1); SCHED; LDA(At, 0, 0); STAGE(SA(1, 1), a1 + hstep, voffA);
;       WAIT_V(8); WAIT_L(0); BAR; MMA(0, 0, At, B0); MMA(0, 1, At, B1); BAR; SCHED;
;       LDA(At, 0, 1); STAGE(SB(0, 0), b2, voffB); STAGE(SB(0, 1), b2 + hstep, voffB); STAGE(SA(0, 0), a2, voffA);
;       WAIT_V(8); WAIT_L(0); BAR; MMA(1, 0, At, B0); MMA(1, 1, At, B1); BAR; SCHED;
.LBB0_141:
	s_add_u32 s22, s46, s20
	s_addc_u32 s23, s47, s21
	s_add_u32 s22, s22, 0x520e100
	s_addc_u32 s23, s23, 0
	s_add_u32 s49, s44, s20
	s_addc_u32 s50, s45, s21
	s_add_i32 s51, 0, 0x10000
	s_cmpk_eq_i32 s20, 0x700
	s_cselect_b32 s27, s42, s23
	s_cselect_b32 s26, s9, s22
	v_add_u32_e32 v177, s51, v148
	s_cselect_b32 s23, s43, s50
	s_cselect_b32 s22, s11, s49
	s_add_i32 s49, 0, 0x14000
	ds_read_b128 v[152:155], v177
	ds_read_b128 v[178:181], v177 offset:1024
	ds_read_b128 v[182:185], v177 offset:2048
	ds_read_b128 v[186:189], v177 offset:3072
	v_add_u32_e32 v177, s49, v148
	ds_read_b128 v[190:193], v177
	ds_read_b128 v[194:197], v177 offset:1024
	ds_read_b128 v[198:201], v177 offset:2048
	ds_read_b128 v[202:205], v177 offset:3072
	v_lshl_add_u64 v[238:239], v[146:147], 0, s[20:21]
	s_add_i32 m0, s17, 0xc000
	ds_read_b128 v[206:209], v151
	ds_read_b128 v[210:213], v151 offset:1024
	ds_read_b128 v[214:217], v151 offset:2048
	ds_read_b128 v[218:221], v151 offset:3072
	ds_read_b128 v[222:225], v151 offset:4096
	ds_read_b128 v[226:229], v151 offset:5120
	ds_read_b128 v[230:233], v151 offset:6144
	ds_read_b128 v[234:237], v151 offset:7168
	global_load_lds_dwordx4 v[238:239], off
	v_lshl_add_u64 v[238:239], v[144:145], 0, s[20:21]
	s_add_i32 m0, s17, 0xe000
	s_nop 0
	global_load_lds_dwordx4 v[238:239], off
	s_waitcnt vmcnt(8)
	s_waitcnt lgkmcnt(0)
	s_barrier
	s_waitcnt lgkmcnt(0)
	v_mfma_f32_16x16x32_f16 v[130:133], v[152:155], v[206:209], v[130:133]
	v_mfma_f32_16x16x32_f16 v[126:129], v[182:185], v[206:209], v[126:129]
	v_mfma_f32_16x16x32_f16 v[114:117], v[152:155], v[214:217], v[114:117]
	v_mfma_f32_16x16x32_f16 v[110:113], v[182:185], v[214:217], v[110:113]
	v_mfma_f32_16x16x32_f16 v[98:101], v[152:155], v[222:225], v[98:101]
	v_mfma_f32_16x16x32_f16 v[94:97], v[182:185], v[222:225], v[94:97]
	v_mfma_f32_16x16x32_f16 v[82:85], v[152:155], v[230:233], v[82:85]
	v_mfma_f32_16x16x32_f16 v[78:81], v[182:185], v[230:233], v[78:81]
	v_mfma_f32_16x16x32_f16 v[130:133], v[178:181], v[210:213], v[130:133]
	v_mfma_f32_16x16x32_f16 v[126:129], v[186:189], v[210:213], v[126:129]
	v_mfma_f32_16x16x32_f16 v[114:117], v[178:181], v[218:221], v[114:117]
	v_mfma_f32_16x16x32_f16 v[110:113], v[186:189], v[218:221], v[110:113]
	v_mfma_f32_16x16x32_f16 v[98:101], v[178:181], v[226:229], v[98:101]
	v_mfma_f32_16x16x32_f16 v[94:97], v[186:189], v[226:229], v[94:97]
	v_mfma_f32_16x16x32_f16 v[82:85], v[178:181], v[234:237], v[82:85]
	v_mfma_f32_16x16x32_f16 v[78:81], v[186:189], v[234:237], v[78:81]
	v_mfma_f32_16x16x32_f16 v[122:125], v[190:193], v[206:209], v[122:125]
	v_mfma_f32_16x16x32_f16 v[118:121], v[198:201], v[206:209], v[118:121]
	v_mfma_f32_16x16x32_f16 v[106:109], v[190:193], v[214:217], v[106:109]
	v_mfma_f32_16x16x32_f16 v[102:105], v[198:201], v[214:217], v[102:105]
	v_mfma_f32_16x16x32_f16 v[90:93], v[190:193], v[222:225], v[90:93]
	v_mfma_f32_16x16x32_f16 v[86:89], v[198:201], v[222:225], v[86:89]
	v_mfma_f32_16x16x32_f16 v[74:77], v[190:193], v[230:233], v[74:77]
	v_mfma_f32_16x16x32_f16 v[70:73], v[198:201], v[230:233], v[70:73]
	v_mfma_f32_16x16x32_f16 v[122:125], v[194:197], v[210:213], v[122:125]
	v_mfma_f32_16x16x32_f16 v[118:121], v[202:205], v[210:213], v[118:121]
	v_mfma_f32_16x16x32_f16 v[106:109], v[194:197], v[218:221], v[106:109]
	v_mfma_f32_16x16x32_f16 v[102:105], v[202:205], v[218:221], v[102:105]
	v_mfma_f32_16x16x32_f16 v[90:93], v[194:197], v[226:229], v[90:93]
	v_mfma_f32_16x16x32_f16 v[86:89], v[202:205], v[226:229], v[86:89]
	v_mfma_f32_16x16x32_f16 v[74:77], v[194:197], v[234:237], v[74:77]
	v_mfma_f32_16x16x32_f16 v[70:73], v[202:205], v[234:237], v[70:73]
	s_barrier
	s_add_i32 s50, s51, s30
	v_lshl_add_u64 v[238:239], s[22:23], 0, v[0:1]
	s_mov_b32 m0, s50
	ds_read_b128 v[206:209], v151 offset:16384
	ds_read_b128 v[210:213], v151 offset:17408
	ds_read_b128 v[214:217], v151 offset:18432
	ds_read_b128 v[218:221], v151 offset:19456
	ds_read_b128 v[222:225], v151 offset:20480
	ds_read_b128 v[226:229], v151 offset:21504
	ds_read_b128 v[230:233], v151 offset:22528
	ds_read_b128 v[234:237], v151 offset:23552
	global_load_lds_dwordx4 v[238:239], off
	s_add_i32 m0, s50, 0x2000
	s_add_u32 s50, s22, 0x40000
	v_lshl_add_u64 v[240:241], s[22:23], 0, v[2:3]
	s_addc_u32 s51, s23, 0
	s_add_i32 s49, s49, s30
	global_load_lds_dwordx4 v[240:241], off
	v_lshl_add_u64 v[242:243], s[50:51], 0, v[0:1]
	s_mov_b32 m0, s49
	v_lshl_add_u64 v[244:245], s[26:27], 0, v[134:135]
	global_load_lds_dwordx4 v[242:243], off
	v_lshl_add_u64 v[242:243], s[50:51], 0, v[2:3]
	s_add_i32 m0, s49, 0x2000
	s_nop 0
	global_load_lds_dwordx4 v[242:243], off
	v_lshl_add_u64 v[242:243], s[26:27], 0, v[138:139]
	s_mov_b32 m0, s17
	s_nop 0
	global_load_lds_dwordx4 v[242:243], off
	s_mov_b32 m0, s19
	s_nop 0
	global_load_lds_dwordx4 v[244:245], off
	s_waitcnt vmcnt(8)
	s_waitcnt lgkmcnt(0)
	s_barrier
; #define STAGE(bufoff, gbase, voff) do { _Pragma("unroll") for (int _i = 0; _i < 2; ++_i) \
;     __builtin_amdgcn_global_load_lds((const unsigned*)((const char*)(gbase) + (voff)[_i]), (LAS unsigned*)(lds + (bufoff) + ldsw + _i * 8192), 16, 0, 0); } while (0)
; #define LDA(dst, b, h) do { _Pragma("unroll") for (int m = 0; m < 4; ++m) _Pragma("unroll") for (int k = 0; k < 2; ++k) dst[m][k] = *(const LAS half8*)(lds + SA(b, h) + aoff + m * 2048 + k * 1024); } while (0)
; #define LDB(dst, b, h) do { _Pragma("unroll") for (int n = 0; n < 2; ++n) _Pragma("unroll") for (int k = 0; k < 2; ++k) dst[n][k] = *(const LAS half8*)(lds + SB(b, h) + boff + n * 2048 + k * 1024); } while (0)
; #define MMA(ai, bj, At_, Bt_) do { __builtin_amdgcn_s_setprio(1); \
;     _Pragma("unroll") for (int m = 0; m < 4; ++m) _Pragma("unroll") for (int n = 0; n < 2; ++n) _Pragma("unroll") for (int k = 0; k < 2; ++k) \
;       acc[ai][bj][m][n] = MFMA16(Bt_[n][k], At_[m][k], acc[ai][bj][m][n]); \
;     __builtin_amdgcn_s_setprio(0); } while (0)
; #define WAIT_V(n) asm volatile("s_waitcnt vmcnt(" #n ")" ::: "memory")
; #define WAIT_L(n) asm volatile("s_waitcnt lgkmcnt(" #n ")" ::: "memory")
; #define BAR __builtin_amdgcn_s_barrier()
; #define SCHED __builtin_amdgcn_sched_barrier(0)
; template <int EPI>
; DI void gemm_phase(const int wid_s, const h16* __restrict__ A, const h16* __restrict__ Bt, const int N, const int K, const EpiArgs ea) {
;     ...
;       WAIT_V(8); WAIT_L(0); BAR; MMA(1, 0, At, B0); MMA(1, 1, At, B1); BAR; SCHED;
;       LDB(B0, 1, 0); LDB(B1, 1, 1); SCHED; LDA(At, 1, 0); STAGE(SA(0, 1), a2 + hstep, voffA);
;       WAIT_V(8); WAIT_L(0); BAR; MMA(0, 0, At, B0); MMA(0, 1, At, B1); BAR; SCHED;
	s_waitcnt lgkmcnt(0)
	v_mfma_f32_16x16x32_f16 v[66:69], v[152:155], v[206:209], v[66:69]
	v_mfma_f32_16x16x32_f16 v[62:65], v[182:185], v[206:209], v[62:65]
	v_mfma_f32_16x16x32_f16 v[50:53], v[152:155], v[214:217], v[50:53]
	v_mfma_f32_16x16x32_f16 v[46:49], v[182:185], v[214:217], v[46:49]
	v_mfma_f32_16x16x32_f16 v[34:37], v[152:155], v[222:225], v[34:37]
	v_mfma_f32_16x16x32_f16 v[30:33], v[182:185], v[222:225], v[30:33]
	v_mfma_f32_16x16x32_f16 v[18:21], v[152:155], v[230:233], v[18:21]
	v_mfma_f32_16x16x32_f16 v[14:17], v[182:185], v[230:233], v[14:17]
	v_mfma_f32_16x16x32_f16 v[66:69], v[178:181], v[210:213], v[66:69]
	v_mfma_f32_16x16x32_f16 v[62:65], v[186:189], v[210:213], v[62:65]
	v_mfma_f32_16x16x32_f16 v[50:53], v[178:181], v[218:221], v[50:53]
	v_mfma_f32_16x16x32_f16 v[46:49], v[186:189], v[218:221], v[46:49]
	v_mfma_f32_16x16x32_f16 v[34:37], v[178:181], v[226:229], v[34:37]
	v_mfma_f32_16x16x32_f16 v[30:33], v[186:189], v[226:229], v[30:33]
	v_mfma_f32_16x16x32_f16 v[18:21], v[178:181], v[234:237], v[18:21]
	v_mfma_f32_16x16x32_f16 v[14:17], v[186:189], v[234:237], v[14:17]
	v_mfma_f32_16x16x32_f16 v[58:61], v[190:193], v[206:209], v[58:61]
	v_mfma_f32_16x16x32_f16 v[54:57], v[198:201], v[206:209], v[54:57]
	v_mfma_f32_16x16x32_f16 v[42:45], v[190:193], v[214:217], v[42:45]
	v_mfma_f32_16x16x32_f16 v[38:41], v[198:201], v[214:217], v[38:41]
	v_mfma_f32_16x16x32_f16 v[26:29], v[190:193], v[222:225], v[26:29]
	v_mfma_f32_16x16x32_f16 v[22:25], v[198:201], v[222:225], v[22:25]
	v_mfma_f32_16x16x32_f16 v[10:13], v[190:193], v[230:233], v[10:13]
	v_mfma_f32_16x16x32_f16 v[6:9], v[198:201], v[230:233], v[6:9]
	v_mfma_f32_16x16x32_f16 v[58:61], v[194:197], v[210:213], v[58:61]
	v_mfma_f32_16x16x32_f16 v[54:57], v[202:205], v[210:213], v[54:57]
	v_mfma_f32_16x16x32_f16 v[42:45], v[194:197], v[218:221], v[42:45]
	v_mfma_f32_16x16x32_f16 v[38:41], v[202:205], v[218:221], v[38:41]
	v_mfma_f32_16x16x32_f16 v[26:29], v[194:197], v[226:229], v[26:29]
	v_mfma_f32_16x16x32_f16 v[22:25], v[202:205], v[226:229], v[22:25]
	v_mfma_f32_16x16x32_f16 v[10:13], v[194:197], v[234:237], v[10:13]
	v_mfma_f32_16x16x32_f16 v[6:9], v[202:205], v[234:237], v[6:9]
	s_barrier
	s_add_i32 s49, 0, 0x18000
	v_add_u32_e32 v177, s49, v148
	s_add_i32 s50, 0, 0x1c000
	ds_read_b128 v[152:155], v177
	ds_read_b128 v[178:181], v177 offset:1024
	ds_read_b128 v[182:185], v177 offset:2048
	ds_read_b128 v[186:189], v177 offset:3072
	v_add_u32_e32 v177, s50, v148
	ds_read_b128 v[190:193], v177
	ds_read_b128 v[194:197], v177 offset:1024
	ds_read_b128 v[198:201], v177 offset:2048
	ds_read_b128 v[202:205], v177 offset:3072
	s_add_u32 s26, s26, 0x40000
	s_addc_u32 s27, s27, 0
	s_mov_b32 m0, s31
	v_lshl_add_u64 v[246:247], s[26:27], 0, v[138:139]
	ds_read_b128 v[206:209], v151 offset:32768
	ds_read_b128 v[210:213], v151 offset:33792
	ds_read_b128 v[214:217], v151 offset:34816
	ds_read_b128 v[218:221], v151 offset:35840
	ds_read_b128 v[222:225], v151 offset:36864
	ds_read_b128 v[226:229], v151 offset:37888
	ds_read_b128 v[230:233], v151 offset:38912
	ds_read_b128 v[234:237], v151 offset:39936
	global_load_lds_dwordx4 v[246:247], off
	v_lshl_add_u64 v[246:247], s[26:27], 0, v[134:135]
	s_mov_b32 m0, s38
	s_nop 0
	global_load_lds_dwordx4 v[246:247], off
	s_waitcnt vmcnt(8)
	s_waitcnt lgkmcnt(0)
	s_barrier
	s_waitcnt lgkmcnt(0)
	v_mfma_f32_16x16x32_f16 v[130:133], v[152:155], v[206:209], v[130:133]
	v_mfma_f32_16x16x32_f16 v[126:129], v[182:185], v[206:209], v[126:129]
	v_mfma_f32_16x16x32_f16 v[114:117], v[152:155], v[214:217], v[114:117]
	v_mfma_f32_16x16x32_f16 v[110:113], v[182:185], v[214:217], v[110:113]
	v_mfma_f32_16x16x32_f16 v[98:101], v[152:155], v[222:225], v[98:101]
	v_mfma_f32_16x16x32_f16 v[94:97], v[182:185], v[222:225], v[94:97]
	v_mfma_f32_16x16x32_f16 v[82:85], v[152:155], v[230:233], v[82:85]
	v_mfma_f32_16x16x32_f16 v[78:81], v[182:185], v[230:233], v[78:81]
	v_mfma_f32_16x16x32_f16 v[130:133], v[178:181], v[210:213], v[130:133]
	v_mfma_f32_16x16x32_f16 v[126:129], v[186:189], v[210:213], v[126:129]
	v_mfma_f32_16x16x32_f16 v[114:117], v[178:181], v[218:221], v[114:117]
	v_mfma_f32_16x16x32_f16 v[110:113], v[186:189], v[218:221], v[110:113]
	v_mfma_f32_16x16x32_f16 v[98:101], v[178:181], v[226:229], v[98:101]
	v_mfma_f32_16x16x32_f16 v[94:97], v[186:189], v[226:229], v[94:97]
	v_mfma_f32_16x16x32_f16 v[82:85], v[178:181], v[234:237], v[82:85]
	v_mfma_f32_16x16x32_f16 v[78:81], v[186:189], v[234:237], v[78:81]
	v_mfma_f32_16x16x32_f16 v[122:125], v[190:193], v[206:209], v[122:125]
	v_mfma_f32_16x16x32_f16 v[118:121], v[198:201], v[206:209], v[118:121]
	v_mfma_f32_16x16x32_f16 v[106:109], v[190:193], v[214:217], v[106:109]
	v_mfma_f32_16x16x32_f16 v[102:105], v[198:201], v[214:217], v[102:105]
	v_mfma_f32_16x16x32_f16 v[90:93], v[190:193], v[222:225], v[90:93]
	v_mfma_f32_16x16x32_f16 v[86:89], v[198:201], v[222:225], v[86:89]
	v_mfma_f32_16x16x32_f16 v[74:77], v[190:193], v[230:233], v[74:77]
	v_mfma_f32_16x16x32_f16 v[70:73], v[198:201], v[230:233], v[70:73]
	v_mfma_f32_16x16x32_f16 v[122:125], v[194:197], v[210:213], v[122:125]
	v_mfma_f32_16x16x32_f16 v[118:121], v[202:205], v[210:213], v[118:121]
	v_mfma_f32_16x16x32_f16 v[106:109], v[194:197], v[218:221], v[106:109]
	v_mfma_f32_16x16x32_f16 v[102:105], v[202:205], v[218:221], v[102:105]
	v_mfma_f32_16x16x32_f16 v[90:93], v[194:197], v[226:229], v[90:93]
	v_mfma_f32_16x16x32_f16 v[86:89], v[202:205], v[226:229], v[86:89]
	v_mfma_f32_16x16x32_f16 v[74:77], v[194:197], v[234:237], v[74:77]
	v_mfma_f32_16x16x32_f16 v[70:73], v[202:205], v[234:237], v[70:73]
	s_barrier
; #define STAGE(bufoff, gbase, voff) do { _Pragma("unroll") for (int _i = 0; _i < 2; ++_i) \
;     __builtin_amdgcn_global_load_lds((const unsigned*)((const char*)(gbase) + (voff)[_i]), (LAS unsigned*)(lds + (bufoff) + ldsw + _i * 8192), 16, 0, 0); } while (0)
; #define LDA(dst, b, h) do { _Pragma("unroll") for (int m = 0; m < 4; ++m) _Pragma("unroll") for (int k = 0; k < 2; ++k) dst[m][k] = *(const LAS half8*)(lds + SA(b, h) + aoff + m * 2048 + k * 1024); } while (0)
; #define MMA(ai, bj, At_, Bt_) do { __builtin_amdgcn_s_setprio(1); \
;     _Pragma("unroll") for (int m = 0; m < 4; ++m) _Pragma("unroll") for (int n = 0; n < 2; ++n) _Pragma("unroll") for (int k = 0; k < 2; ++k) \
;       acc[ai][bj][m][n] = MFMA16(Bt_[n][k], At_[m][k], acc[ai][bj][m][n]); \
;     __builtin_amdgcn_s_setprio(0); } while (0)
; #define WAIT_V(n) asm volatile("s_waitcnt vmcnt(" #n ")" ::: "memory")
; #define WAIT_L(n) asm volatile("s_waitcnt lgkmcnt(" #n ")" ::: "memory")
; #define BAR __builtin_amdgcn_s_barrier()
; #define SCHED __builtin_amdgcn_sched_barrier(0)
; template <int EPI>
; DI void gemm_phase(const int wid_s, const h16* __restrict__ A, const h16* __restrict__ Bt, const int N, const int K, const EpiArgs ea) {
;     ...
;     for (int t = 0; t < nt; t += 2) {
;     ...
;       LDA(At, 1, 1); STAGE(SB(1, 0), b3, voffB); STAGE(SB(1, 1), b3 + hstep, voffB); STAGE(SA(1, 0), a3, voffA);
;       WAIT_V(8); WAIT_L(0); BAR; MMA(1, 0, At, B0); MMA(1, 1, At, B1); BAR; SCHED;
;     }
	s_add_i32 s26, s49, s30
	v_lshl_add_u64 v[238:239], v[238:239], 0, s[36:37]
	s_mov_b32 m0, s26
	ds_read_b128 v[206:209], v151 offset:49152
	ds_read_b128 v[210:213], v151 offset:50176
	ds_read_b128 v[214:217], v151 offset:51200
	ds_read_b128 v[218:221], v151 offset:52224
	ds_read_b128 v[222:225], v151 offset:53248
	ds_read_b128 v[226:229], v151 offset:54272
	ds_read_b128 v[230:233], v151 offset:55296
	ds_read_b128 v[234:237], v151 offset:56320
	global_load_lds_dwordx4 v[238:239], off
	s_add_i32 m0, s26, 0x2000
	s_add_u32 s22, s22, 0x40080
	v_lshl_add_u64 v[238:239], v[240:241], 0, s[36:37]
	s_addc_u32 s23, s23, 0
	s_add_i32 s26, s50, s30
	global_load_lds_dwordx4 v[238:239], off
	v_lshl_add_u64 v[238:239], s[22:23], 0, v[0:1]
	s_mov_b32 m0, s26
	s_nop 0
	global_load_lds_dwordx4 v[238:239], off
	v_lshl_add_u64 v[238:239], s[22:23], 0, v[2:3]
	s_add_i32 m0, s26, 0x2000
	s_nop 0
	global_load_lds_dwordx4 v[238:239], off
	v_lshl_add_u64 v[238:239], v[242:243], 0, s[36:37]
	s_mov_b32 m0, s40
	s_nop 0
	global_load_lds_dwordx4 v[238:239], off
	v_lshl_add_u64 v[238:239], v[244:245], 0, s[36:37]
	s_mov_b32 m0, s41
	s_nop 0
	global_load_lds_dwordx4 v[238:239], off
	s_waitcnt vmcnt(8)
	s_waitcnt lgkmcnt(0)
	s_barrier
	s_waitcnt lgkmcnt(0)
	v_mfma_f32_16x16x32_f16 v[66:69], v[152:155], v[206:209], v[66:69]
	v_mfma_f32_16x16x32_f16 v[62:65], v[182:185], v[206:209], v[62:65]
	v_mfma_f32_16x16x32_f16 v[50:53], v[152:155], v[214:217], v[50:53]
	v_mfma_f32_16x16x32_f16 v[46:49], v[182:185], v[214:217], v[46:49]
	v_mfma_f32_16x16x32_f16 v[34:37], v[152:155], v[222:225], v[34:37]
	v_mfma_f32_16x16x32_f16 v[30:33], v[182:185], v[222:225], v[30:33]
	v_mfma_f32_16x16x32_f16 v[18:21], v[152:155], v[230:233], v[18:21]
	v_mfma_f32_16x16x32_f16 v[14:17], v[182:185], v[230:233], v[14:17]
	v_mfma_f32_16x16x32_f16 v[66:69], v[178:181], v[210:213], v[66:69]
	v_mfma_f32_16x16x32_f16 v[62:65], v[186:189], v[210:213], v[62:65]
	v_mfma_f32_16x16x32_f16 v[50:53], v[178:181], v[218:221], v[50:53]
	v_mfma_f32_16x16x32_f16 v[46:49], v[186:189], v[218:221], v[46:49]
	v_mfma_f32_16x16x32_f16 v[34:37], v[178:181], v[226:229], v[34:37]
	v_mfma_f32_16x16x32_f16 v[30:33], v[186:189], v[226:229], v[30:33]
	v_mfma_f32_16x16x32_f16 v[18:21], v[178:181], v[234:237], v[18:21]
	v_mfma_f32_16x16x32_f16 v[14:17], v[186:189], v[234:237], v[14:17]
	v_mfma_f32_16x16x32_f16 v[58:61], v[190:193], v[206:209], v[58:61]
	v_mfma_f32_16x16x32_f16 v[54:57], v[198:201], v[206:209], v[54:57]
	v_mfma_f32_16x16x32_f16 v[42:45], v[190:193], v[214:217], v[42:45]
	v_mfma_f32_16x16x32_f16 v[38:41], v[198:201], v[214:217], v[38:41]
	v_mfma_f32_16x16x32_f16 v[26:29], v[190:193], v[222:225], v[26:29]
	v_mfma_f32_16x16x32_f16 v[22:25], v[198:201], v[222:225], v[22:25]
	v_mfma_f32_16x16x32_f16 v[10:13], v[190:193], v[230:233], v[10:13]
	v_mfma_f32_16x16x32_f16 v[6:9], v[198:201], v[230:233], v[6:9]
	v_mfma_f32_16x16x32_f16 v[58:61], v[194:197], v[210:213], v[58:61]
	v_mfma_f32_16x16x32_f16 v[54:57], v[202:205], v[210:213], v[54:57]
	v_mfma_f32_16x16x32_f16 v[42:45], v[194:197], v[218:221], v[42:45]
	v_mfma_f32_16x16x32_f16 v[38:41], v[202:205], v[218:221], v[38:41]
	v_mfma_f32_16x16x32_f16 v[26:29], v[194:197], v[226:229], v[26:29]
	v_mfma_f32_16x16x32_f16 v[22:25], v[202:205], v[226:229], v[22:25]
	v_mfma_f32_16x16x32_f16 v[10:13], v[194:197], v[234:237], v[10:13]
	v_mfma_f32_16x16x32_f16 v[6:9], v[202:205], v[234:237], v[6:9]
	s_barrier
	s_add_i32 s48, s48, 2
	s_add_u32 s20, s20, 0x100
	s_addc_u32 s21, s21, 0
	s_cmp_gt_u32 s48, 13
	s_cbranch_scc0 .LBB0_141
	s_and_b64 vcc, exec, s[4:5]
	s_cbranch_vccz .LBB0_144
	s_barrier

; #define STAGE(bufoff, gbase, voff) do { _Pragma("unroll") for (int _i = 0; _i < 2; ++_i) \
;     __builtin_amdgcn_global_load_lds((const unsigned*)((const char*)(gbase) + (voff)[_i]), (LAS unsigned*)(lds + (bufoff) + ldsw + _i * 8192), 16, 0, 0); } while (0)
; #define LDA(dst, b, h) do { _Pragma("unroll") for (int m = 0; m < 4; ++m) _Pragma("unroll") for (int k = 0; k < 2; ++k) dst[m][k] = *(const LAS half8*)(lds + SA(b, h) + aoff + m * 2048 + k * 1024); } while (0)
; #define LDB(dst, b, h) do { _Pragma("unroll") for (int n = 0; n < 2; ++n) _Pragma("unroll") for (int k = 0; k < 2; ++k) dst[n][k] = *(const LAS half8*)(lds + SB(b, h) + boff + n * 2048 + k * 1024); } while (0)
; #define MMA(ai, bj, At_, Bt_) do { __builtin_amdgcn_s_setprio(1); \
;     _Pragma("unroll") for (int m = 0; m < 4; ++m) _Pragma("unroll") for (int n = 0; n < 2; ++n) _Pragma("unroll") for (int k = 0; k < 2; ++k) \
;       acc[ai][bj][m][n] = MFMA16(Bt_[n][k], At_[m][k], acc[ai][bj][m][n]); \
;     __builtin_amdgcn_s_setprio(0); } while (0)
; #define WAIT_V(n) asm volatile("s_waitcnt vmcnt(" #n ")" ::: "memory")
; #define WAIT_L(n) asm volatile("s_waitcnt lgkmcnt(" #n ")" ::: "memory")
; #define BAR __builtin_amdgcn_s_barrier()
; #define SCHED __builtin_amdgcn_sched_barrier(0)
; template <int EPI>
; DI void gemm_phase(const int wid_s, const h16* __restrict__ A, const h16* __restrict__ Bt, const int N, const int K, const EpiArgs ea) {
;     ...
;       const char* a1 = cA + (size_t)(t + 1) * kstep;
;       const char* a2 = last ? nA : cA + (size_t)(t + 2) * kstep; const char* b2 = last ? nB : cB + (size_t)(t + 2) * kstep;
;       const char* a3 = a2 + kstep; const char* b3 = b2 + kstep;
;       LDB(B0, 0, 0); LDB(B1, 0, 1); SCHED; LDA(At, 0, 0); STAGE(SA(1, 1), a1 + hstep, voffA);
;       WAIT_V(8); WAIT_L(0); BAR; MMA(0, 0, At, B0); MMA(0, 1, At, B1); BAR; SCHED;
;       LDA(At, 0, 1); STAGE(SB(0, 0), b2, voffB); STAGE(SB(0, 1), b2 + hstep, voffB); STAGE(SA(0, 0), a2, voffA);
;       WAIT_V(8); WAIT_L(0); BAR; MMA(1, 0, At, B0); MMA(1, 1, At, B1); BAR; SCHED;
.LBB0_175:
	s_add_u32 s22, s20, 0xfffc0080
	s_addc_u32 s23, s21, -1
	s_add_i32 s44, 0, 0x10000
	s_cmp_eq_u32 s43, 12
	s_cselect_b32 s27, s13, s23
	s_cselect_b32 s26, s12, s22
	v_add_u32_e32 v177, s44, v148
	s_cselect_b32 s23, s11, s42
	s_cselect_b32 s22, s9, s41
	s_add_i32 s46, 0, 0x14000
	ds_read_b128 v[144:147], v177
	ds_read_b128 v[152:155], v177 offset:1024
	ds_read_b128 v[178:181], v177 offset:2048
	ds_read_b128 v[182:185], v177 offset:3072
	v_add_u32_e32 v177, s46, v148
	ds_read_b128 v[186:189], v177
	ds_read_b128 v[190:193], v177 offset:1024
	ds_read_b128 v[194:197], v177 offset:2048
	ds_read_b128 v[198:201], v177 offset:3072
	v_lshl_add_u64 v[234:235], s[20:21], 0, v[142:143]
	s_add_i32 m0, s17, 0xc000
	ds_read_b128 v[202:205], v151
	ds_read_b128 v[206:209], v151 offset:1024
	ds_read_b128 v[210:213], v151 offset:2048
	ds_read_b128 v[214:217], v151 offset:3072
	ds_read_b128 v[218:221], v151 offset:4096
	ds_read_b128 v[222:225], v151 offset:5120
	ds_read_b128 v[226:229], v151 offset:6144
	ds_read_b128 v[230:233], v151 offset:7168
	global_load_lds_dwordx4 v[234:235], off
	v_lshl_add_u64 v[234:235], s[20:21], 0, v[140:141]
	s_add_i32 m0, s17, 0xe000
	s_nop 0
	global_load_lds_dwordx4 v[234:235], off
	s_waitcnt vmcnt(8)
	s_waitcnt lgkmcnt(0)
	s_barrier
	s_waitcnt lgkmcnt(0)
	v_mfma_f32_16x16x32_f16 v[130:133], v[144:147], v[202:205], v[130:133]
	v_mfma_f32_16x16x32_f16 v[126:129], v[178:181], v[202:205], v[126:129]
	v_mfma_f32_16x16x32_f16 v[114:117], v[144:147], v[210:213], v[114:117]
	v_mfma_f32_16x16x32_f16 v[110:113], v[178:181], v[210:213], v[110:113]
	v_mfma_f32_16x16x32_f16 v[98:101], v[144:147], v[218:221], v[98:101]
	v_mfma_f32_16x16x32_f16 v[94:97], v[178:181], v[218:221], v[94:97]
	v_mfma_f32_16x16x32_f16 v[82:85], v[144:147], v[226:229], v[82:85]
	v_mfma_f32_16x16x32_f16 v[78:81], v[178:181], v[226:229], v[78:81]
	v_mfma_f32_16x16x32_f16 v[130:133], v[152:155], v[206:209], v[130:133]
	v_mfma_f32_16x16x32_f16 v[126:129], v[182:185], v[206:209], v[126:129]
	v_mfma_f32_16x16x32_f16 v[114:117], v[152:155], v[214:217], v[114:117]
	v_mfma_f32_16x16x32_f16 v[110:113], v[182:185], v[214:217], v[110:113]
	v_mfma_f32_16x16x32_f16 v[98:101], v[152:155], v[222:225], v[98:101]
	v_mfma_f32_16x16x32_f16 v[94:97], v[182:185], v[222:225], v[94:97]
	v_mfma_f32_16x16x32_f16 v[82:85], v[152:155], v[230:233], v[82:85]
	v_mfma_f32_16x16x32_f16 v[78:81], v[182:185], v[230:233], v[78:81]
	v_mfma_f32_16x16x32_f16 v[122:125], v[186:189], v[202:205], v[122:125]
	v_mfma_f32_16x16x32_f16 v[118:121], v[194:197], v[202:205], v[118:121]
	v_mfma_f32_16x16x32_f16 v[106:109], v[186:189], v[210:213], v[106:109]
	v_mfma_f32_16x16x32_f16 v[102:105], v[194:197], v[210:213], v[102:105]
	v_mfma_f32_16x16x32_f16 v[90:93], v[186:189], v[218:221], v[90:93]
	v_mfma_f32_16x16x32_f16 v[86:89], v[194:197], v[218:221], v[86:89]
	v_mfma_f32_16x16x32_f16 v[74:77], v[186:189], v[226:229], v[74:77]
	v_mfma_f32_16x16x32_f16 v[70:73], v[194:197], v[226:229], v[70:73]
	v_mfma_f32_16x16x32_f16 v[122:125], v[190:193], v[206:209], v[122:125]
	v_mfma_f32_16x16x32_f16 v[118:121], v[198:201], v[206:209], v[118:121]
	v_mfma_f32_16x16x32_f16 v[106:109], v[190:193], v[214:217], v[106:109]
	v_mfma_f32_16x16x32_f16 v[102:105], v[198:201], v[214:217], v[102:105]
	v_mfma_f32_16x16x32_f16 v[90:93], v[190:193], v[222:225], v[90:93]
	v_mfma_f32_16x16x32_f16 v[86:89], v[198:201], v[222:225], v[86:89]
	v_mfma_f32_16x16x32_f16 v[74:77], v[190:193], v[230:233], v[74:77]
	v_mfma_f32_16x16x32_f16 v[70:73], v[198:201], v[230:233], v[70:73]
	s_barrier
	s_add_i32 s44, s44, s30
	v_lshl_add_u64 v[234:235], s[22:23], 0, v[0:1]
	s_mov_b32 m0, s44
	ds_read_b128 v[202:205], v151 offset:16384
	ds_read_b128 v[206:209], v151 offset:17408
	ds_read_b128 v[210:213], v151 offset:18432
	ds_read_b128 v[214:217], v151 offset:19456
	ds_read_b128 v[218:221], v151 offset:20480
	ds_read_b128 v[222:225], v151 offset:21504
	ds_read_b128 v[226:229], v151 offset:22528
	ds_read_b128 v[230:233], v151 offset:23552
	global_load_lds_dwordx4 v[234:235], off
	s_add_i32 m0, s44, 0x2000
	s_add_u32 s44, s22, 0x40000
	v_lshl_add_u64 v[236:237], s[22:23], 0, v[138:139]
	s_addc_u32 s45, s23, 0
	s_add_i32 s46, s46, s30
	global_load_lds_dwordx4 v[236:237], off
	v_lshl_add_u64 v[238:239], s[44:45], 0, v[0:1]
	s_mov_b32 m0, s46
	v_lshl_add_u64 v[240:241], s[26:27], 0, v[134:135]
	global_load_lds_dwordx4 v[238:239], off
	v_lshl_add_u64 v[238:239], s[44:45], 0, v[138:139]
	s_add_i32 m0, s46, 0x2000
	s_nop 0
	global_load_lds_dwordx4 v[238:239], off
	v_lshl_add_u64 v[238:239], s[26:27], 0, v[2:3]
	s_mov_b32 m0, s17
	s_nop 0
	global_load_lds_dwordx4 v[238:239], off
	s_mov_b32 m0, s19
	s_nop 0
	global_load_lds_dwordx4 v[240:241], off
	s_waitcnt vmcnt(8)
	s_waitcnt lgkmcnt(0)
	s_barrier
; #define STAGE(bufoff, gbase, voff) do { _Pragma("unroll") for (int _i = 0; _i < 2; ++_i) \
;     __builtin_amdgcn_global_load_lds((const unsigned*)((const char*)(gbase) + (voff)[_i]), (LAS unsigned*)(lds + (bufoff) + ldsw + _i * 8192), 16, 0, 0); } while (0)
; #define LDA(dst, b, h) do { _Pragma("unroll") for (int m = 0; m < 4; ++m) _Pragma("unroll") for (int k = 0; k < 2; ++k) dst[m][k] = *(const LAS half8*)(lds + SA(b, h) + aoff + m * 2048 + k * 1024); } while (0)
; #define LDB(dst, b, h) do { _Pragma("unroll") for (int n = 0; n < 2; ++n) _Pragma("unroll") for (int k = 0; k < 2; ++k) dst[n][k] = *(const LAS half8*)(lds + SB(b, h) + boff + n * 2048 + k * 1024); } while (0)
; #define MMA(ai, bj, At_, Bt_) do { __builtin_amdgcn_s_setprio(1); \
;     _Pragma("unroll") for (int m = 0; m < 4; ++m) _Pragma("unroll") for (int n = 0; n < 2; ++n) _Pragma("unroll") for (int k = 0; k < 2; ++k) \
;       acc[ai][bj][m][n] = MFMA16(Bt_[n][k], At_[m][k], acc[ai][bj][m][n]); \
;     __builtin_amdgcn_s_setprio(0); } while (0)
; #define WAIT_V(n) asm volatile("s_waitcnt vmcnt(" #n ")" ::: "memory")
; #define WAIT_L(n) asm volatile("s_waitcnt lgkmcnt(" #n ")" ::: "memory")
; #define BAR __builtin_amdgcn_s_barrier()
; #define SCHED __builtin_amdgcn_sched_barrier(0)
; template <int EPI>
; DI void gemm_phase(const int wid_s, const h16* __restrict__ A, const h16* __restrict__ Bt, const int N, const int K, const EpiArgs ea) {
;     ...
;       WAIT_V(8); WAIT_L(0); BAR; MMA(1, 0, At, B0); MMA(1, 1, At, B1); BAR; SCHED;
;       LDB(B0, 1, 0); LDB(B1, 1, 1); SCHED; LDA(At, 1, 0); STAGE(SA(0, 1), a2 + hstep, voffA);
;       WAIT_V(8); WAIT_L(0); BAR; MMA(0, 0, At, B0); MMA(0, 1, At, B1); BAR; SCHED;
	s_waitcnt lgkmcnt(0)
	v_mfma_f32_16x16x32_f16 v[66:69], v[144:147], v[202:205], v[66:69]
	v_mfma_f32_16x16x32_f16 v[62:65], v[178:181], v[202:205], v[62:65]
	v_mfma_f32_16x16x32_f16 v[50:53], v[144:147], v[210:213], v[50:53]
	v_mfma_f32_16x16x32_f16 v[46:49], v[178:181], v[210:213], v[46:49]
	v_mfma_f32_16x16x32_f16 v[34:37], v[144:147], v[218:221], v[34:37]
	v_mfma_f32_16x16x32_f16 v[30:33], v[178:181], v[218:221], v[30:33]
	v_mfma_f32_16x16x32_f16 v[18:21], v[144:147], v[226:229], v[18:21]
	v_mfma_f32_16x16x32_f16 v[14:17], v[178:181], v[226:229], v[14:17]
	v_mfma_f32_16x16x32_f16 v[66:69], v[152:155], v[206:209], v[66:69]
	v_mfma_f32_16x16x32_f16 v[62:65], v[182:185], v[206:209], v[62:65]
	v_mfma_f32_16x16x32_f16 v[50:53], v[152:155], v[214:217], v[50:53]
	v_mfma_f32_16x16x32_f16 v[46:49], v[182:185], v[214:217], v[46:49]
	v_mfma_f32_16x16x32_f16 v[34:37], v[152:155], v[222:225], v[34:37]
	v_mfma_f32_16x16x32_f16 v[30:33], v[182:185], v[222:225], v[30:33]
	v_mfma_f32_16x16x32_f16 v[18:21], v[152:155], v[230:233], v[18:21]
	v_mfma_f32_16x16x32_f16 v[14:17], v[182:185], v[230:233], v[14:17]
	v_mfma_f32_16x16x32_f16 v[58:61], v[186:189], v[202:205], v[58:61]
	v_mfma_f32_16x16x32_f16 v[54:57], v[194:197], v[202:205], v[54:57]
	v_mfma_f32_16x16x32_f16 v[42:45], v[186:189], v[210:213], v[42:45]
	v_mfma_f32_16x16x32_f16 v[38:41], v[194:197], v[210:213], v[38:41]
	v_mfma_f32_16x16x32_f16 v[26:29], v[186:189], v[218:221], v[26:29]
	v_mfma_f32_16x16x32_f16 v[22:25], v[194:197], v[218:221], v[22:25]
	v_mfma_f32_16x16x32_f16 v[10:13], v[186:189], v[226:229], v[10:13]
	v_mfma_f32_16x16x32_f16 v[6:9], v[194:197], v[226:229], v[6:9]
	v_mfma_f32_16x16x32_f16 v[58:61], v[190:193], v[206:209], v[58:61]
	v_mfma_f32_16x16x32_f16 v[54:57], v[198:201], v[206:209], v[54:57]
	v_mfma_f32_16x16x32_f16 v[42:45], v[190:193], v[214:217], v[42:45]
	v_mfma_f32_16x16x32_f16 v[38:41], v[198:201], v[214:217], v[38:41]
	v_mfma_f32_16x16x32_f16 v[26:29], v[190:193], v[222:225], v[26:29]
	v_mfma_f32_16x16x32_f16 v[22:25], v[198:201], v[222:225], v[22:25]
	v_mfma_f32_16x16x32_f16 v[10:13], v[190:193], v[230:233], v[10:13]
	v_mfma_f32_16x16x32_f16 v[6:9], v[198:201], v[230:233], v[6:9]
	s_barrier
	s_add_i32 s44, 0, 0x18000
	v_add_u32_e32 v177, s44, v148
	s_add_i32 s45, 0, 0x1c000
	ds_read_b128 v[144:147], v177
	ds_read_b128 v[152:155], v177 offset:1024
	ds_read_b128 v[178:181], v177 offset:2048
	ds_read_b128 v[182:185], v177 offset:3072
	v_add_u32_e32 v177, s45, v148
	ds_read_b128 v[186:189], v177
	ds_read_b128 v[190:193], v177 offset:1024
	ds_read_b128 v[194:197], v177 offset:2048
	ds_read_b128 v[198:201], v177 offset:3072
	s_add_u32 s26, s26, 0x40000
	s_addc_u32 s27, s27, 0
	s_mov_b32 m0, s31
	v_lshl_add_u64 v[242:243], s[26:27], 0, v[2:3]
	ds_read_b128 v[202:205], v151 offset:32768
	ds_read_b128 v[206:209], v151 offset:33792
	ds_read_b128 v[210:213], v151 offset:34816
	ds_read_b128 v[214:217], v151 offset:35840
	ds_read_b128 v[218:221], v151 offset:36864
	ds_read_b128 v[222:225], v151 offset:37888
	ds_read_b128 v[226:229], v151 offset:38912
	ds_read_b128 v[230:233], v151 offset:39936
	global_load_lds_dwordx4 v[242:243], off
	v_lshl_add_u64 v[242:243], s[26:27], 0, v[134:135]
	s_mov_b32 m0, s38
	s_nop 0
	global_load_lds_dwordx4 v[242:243], off
	s_waitcnt vmcnt(8)
	s_waitcnt lgkmcnt(0)
	s_barrier
	s_waitcnt lgkmcnt(0)
	v_mfma_f32_16x16x32_f16 v[130:133], v[144:147], v[202:205], v[130:133]
	v_mfma_f32_16x16x32_f16 v[126:129], v[178:181], v[202:205], v[126:129]
	v_mfma_f32_16x16x32_f16 v[114:117], v[144:147], v[210:213], v[114:117]
	v_mfma_f32_16x16x32_f16 v[110:113], v[178:181], v[210:213], v[110:113]
	v_mfma_f32_16x16x32_f16 v[98:101], v[144:147], v[218:221], v[98:101]
	v_mfma_f32_16x16x32_f16 v[94:97], v[178:181], v[218:221], v[94:97]
	v_mfma_f32_16x16x32_f16 v[82:85], v[144:147], v[226:229], v[82:85]
	v_mfma_f32_16x16x32_f16 v[78:81], v[178:181], v[226:229], v[78:81]
	v_mfma_f32_16x16x32_f16 v[130:133], v[152:155], v[206:209], v[130:133]
	v_mfma_f32_16x16x32_f16 v[126:129], v[182:185], v[206:209], v[126:129]
	v_mfma_f32_16x16x32_f16 v[114:117], v[152:155], v[214:217], v[114:117]
	v_mfma_f32_16x16x32_f16 v[110:113], v[182:185], v[214:217], v[110:113]
	v_mfma_f32_16x16x32_f16 v[98:101], v[152:155], v[222:225], v[98:101]
	v_mfma_f32_16x16x32_f16 v[94:97], v[182:185], v[222:225], v[94:97]
	v_mfma_f32_16x16x32_f16 v[82:85], v[152:155], v[230:233], v[82:85]
	v_mfma_f32_16x16x32_f16 v[78:81], v[182:185], v[230:233], v[78:81]
	v_mfma_f32_16x16x32_f16 v[122:125], v[186:189], v[202:205], v[122:125]
	v_mfma_f32_16x16x32_f16 v[118:121], v[194:197], v[202:205], v[118:121]
	v_mfma_f32_16x16x32_f16 v[106:109], v[186:189], v[210:213], v[106:109]
	v_mfma_f32_16x16x32_f16 v[102:105], v[194:197], v[210:213], v[102:105]
	v_mfma_f32_16x16x32_f16 v[90:93], v[186:189], v[218:221], v[90:93]
	v_mfma_f32_16x16x32_f16 v[86:89], v[194:197], v[218:221], v[86:89]
	v_mfma_f32_16x16x32_f16 v[74:77], v[186:189], v[226:229], v[74:77]
	v_mfma_f32_16x16x32_f16 v[70:73], v[194:197], v[226:229], v[70:73]
	v_mfma_f32_16x16x32_f16 v[122:125], v[190:193], v[206:209], v[122:125]
	v_mfma_f32_16x16x32_f16 v[118:121], v[198:201], v[206:209], v[118:121]
	v_mfma_f32_16x16x32_f16 v[106:109], v[190:193], v[214:217], v[106:109]
	v_mfma_f32_16x16x32_f16 v[102:105], v[198:201], v[214:217], v[102:105]
	v_mfma_f32_16x16x32_f16 v[90:93], v[190:193], v[222:225], v[90:93]
	v_mfma_f32_16x16x32_f16 v[86:89], v[198:201], v[222:225], v[86:89]
	v_mfma_f32_16x16x32_f16 v[74:77], v[190:193], v[230:233], v[74:77]
	v_mfma_f32_16x16x32_f16 v[70:73], v[198:201], v[230:233], v[70:73]
	s_barrier
; #define STAGE(bufoff, gbase, voff) do { _Pragma("unroll") for (int _i = 0; _i < 2; ++_i) \
;     __builtin_amdgcn_global_load_lds((const unsigned*)((const char*)(gbase) + (voff)[_i]), (LAS unsigned*)(lds + (bufoff) + ldsw + _i * 8192), 16, 0, 0); } while (0)
; #define LDA(dst, b, h) do { _Pragma("unroll") for (int m = 0; m < 4; ++m) _Pragma("unroll") for (int k = 0; k < 2; ++k) dst[m][k] = *(const LAS half8*)(lds + SA(b, h) + aoff + m * 2048 + k * 1024); } while (0)
; #define MMA(ai, bj, At_, Bt_) do { __builtin_amdgcn_s_setprio(1); \
;     _Pragma("unroll") for (int m = 0; m < 4; ++m) _Pragma("unroll") for (int n = 0; n < 2; ++n) _Pragma("unroll") for (int k = 0; k < 2; ++k) \
;       acc[ai][bj][m][n] = MFMA16(Bt_[n][k], At_[m][k], acc[ai][bj][m][n]); \
;     __builtin_amdgcn_s_setprio(0); } while (0)
; #define WAIT_V(n) asm volatile("s_waitcnt vmcnt(" #n ")" ::: "memory")
; #define WAIT_L(n) asm volatile("s_waitcnt lgkmcnt(" #n ")" ::: "memory")
; #define BAR __builtin_amdgcn_s_barrier()
; #define SCHED __builtin_amdgcn_sched_barrier(0)
; template <int EPI>
; DI void gemm_phase(const int wid_s, const h16* __restrict__ A, const h16* __restrict__ Bt, const int N, const int K, const EpiArgs ea) {
;     ...
;     for (int t = 0; t < nt; t += 2) {
;     ...
;       LDA(At, 1, 1); STAGE(SB(1, 0), b3, voffB); STAGE(SB(1, 1), b3 + hstep, voffB); STAGE(SA(1, 0), a3, voffA);
;       WAIT_V(8); WAIT_L(0); BAR; MMA(1, 0, At, B0); MMA(1, 1, At, B1); BAR; SCHED;
;     }
	s_add_i32 s26, s44, s30
	v_lshl_add_u64 v[234:235], v[234:235], 0, s[36:37]
	s_mov_b32 m0, s26
	ds_read_b128 v[202:205], v151 offset:49152
	ds_read_b128 v[206:209], v151 offset:50176
	ds_read_b128 v[210:213], v151 offset:51200
	ds_read_b128 v[214:217], v151 offset:52224
	ds_read_b128 v[218:221], v151 offset:53248
	ds_read_b128 v[222:225], v151 offset:54272
	ds_read_b128 v[226:229], v151 offset:55296
	ds_read_b128 v[230:233], v151 offset:56320
	global_load_lds_dwordx4 v[234:235], off
	s_add_i32 m0, s26, 0x2000
	s_add_u32 s22, s22, 0x40080
	v_lshl_add_u64 v[234:235], v[236:237], 0, s[36:37]
	s_addc_u32 s23, s23, 0
	s_add_i32 s26, s45, s30
	global_load_lds_dwordx4 v[234:235], off
	v_lshl_add_u64 v[234:235], s[22:23], 0, v[0:1]
	s_mov_b32 m0, s26
	s_nop 0
	global_load_lds_dwordx4 v[234:235], off
	v_lshl_add_u64 v[234:235], s[22:23], 0, v[138:139]
	s_add_i32 m0, s26, 0x2000
	s_nop 0
	global_load_lds_dwordx4 v[234:235], off
	v_lshl_add_u64 v[234:235], v[238:239], 0, s[36:37]
	s_mov_b32 m0, s39
	s_nop 0
	global_load_lds_dwordx4 v[234:235], off
	v_lshl_add_u64 v[234:235], v[240:241], 0, s[36:37]
	s_mov_b32 m0, s40
	s_nop 0
	global_load_lds_dwordx4 v[234:235], off
	s_waitcnt vmcnt(8)
	s_waitcnt lgkmcnt(0)
	s_barrier
	s_waitcnt lgkmcnt(0)
	v_mfma_f32_16x16x32_f16 v[66:69], v[144:147], v[202:205], v[66:69]
	v_mfma_f32_16x16x32_f16 v[62:65], v[178:181], v[202:205], v[62:65]
	v_mfma_f32_16x16x32_f16 v[50:53], v[144:147], v[210:213], v[50:53]
	v_mfma_f32_16x16x32_f16 v[46:49], v[178:181], v[210:213], v[46:49]
	v_mfma_f32_16x16x32_f16 v[34:37], v[144:147], v[218:221], v[34:37]
	v_mfma_f32_16x16x32_f16 v[30:33], v[178:181], v[218:221], v[30:33]
	v_mfma_f32_16x16x32_f16 v[18:21], v[144:147], v[226:229], v[18:21]
	v_mfma_f32_16x16x32_f16 v[14:17], v[178:181], v[226:229], v[14:17]
	v_mfma_f32_16x16x32_f16 v[66:69], v[152:155], v[206:209], v[66:69]
	v_mfma_f32_16x16x32_f16 v[62:65], v[182:185], v[206:209], v[62:65]
	v_mfma_f32_16x16x32_f16 v[50:53], v[152:155], v[214:217], v[50:53]
	v_mfma_f32_16x16x32_f16 v[46:49], v[182:185], v[214:217], v[46:49]
	v_mfma_f32_16x16x32_f16 v[34:37], v[152:155], v[222:225], v[34:37]
	v_mfma_f32_16x16x32_f16 v[30:33], v[182:185], v[222:225], v[30:33]
	v_mfma_f32_16x16x32_f16 v[18:21], v[152:155], v[230:233], v[18:21]
	v_mfma_f32_16x16x32_f16 v[14:17], v[182:185], v[230:233], v[14:17]
	v_mfma_f32_16x16x32_f16 v[58:61], v[186:189], v[202:205], v[58:61]
	v_mfma_f32_16x16x32_f16 v[54:57], v[194:197], v[202:205], v[54:57]
	v_mfma_f32_16x16x32_f16 v[42:45], v[186:189], v[210:213], v[42:45]
	v_mfma_f32_16x16x32_f16 v[38:41], v[194:197], v[210:213], v[38:41]
	v_mfma_f32_16x16x32_f16 v[26:29], v[186:189], v[218:221], v[26:29]
	v_mfma_f32_16x16x32_f16 v[22:25], v[194:197], v[218:221], v[22:25]
	v_mfma_f32_16x16x32_f16 v[10:13], v[186:189], v[226:229], v[10:13]
	v_mfma_f32_16x16x32_f16 v[6:9], v[194:197], v[226:229], v[6:9]
	v_mfma_f32_16x16x32_f16 v[58:61], v[190:193], v[206:209], v[58:61]
	v_mfma_f32_16x16x32_f16 v[54:57], v[198:201], v[206:209], v[54:57]
	v_mfma_f32_16x16x32_f16 v[42:45], v[190:193], v[214:217], v[42:45]
	v_mfma_f32_16x16x32_f16 v[38:41], v[198:201], v[214:217], v[38:41]
	v_mfma_f32_16x16x32_f16 v[26:29], v[190:193], v[222:225], v[26:29]
	v_mfma_f32_16x16x32_f16 v[22:25], v[198:201], v[222:225], v[22:25]
	v_mfma_f32_16x16x32_f16 v[10:13], v[190:193], v[230:233], v[10:13]
	v_mfma_f32_16x16x32_f16 v[6:9], v[198:201], v[230:233], v[6:9]
	s_barrier
	s_add_i32 s43, s43, 2
	s_add_u32 s41, s41, 0x100
	s_addc_u32 s42, s42, 0
	s_add_u32 s20, s20, 0x100
	s_addc_u32 s21, s21, 0
	s_cmp_gt_u32 s43, 13
	s_cbranch_scc0 .LBB0_175
	s_and_b64 vcc, exec, s[4:5]
	s_cbranch_vccz .LBB0_178
	s_barrier

; #define STAGE(bufoff, gbase, voff) do { _Pragma("unroll") for (int _i = 0; _i < 2; ++_i) \
;     __builtin_amdgcn_global_load_lds((const unsigned*)((const char*)(gbase) + (voff)[_i]), (LAS unsigned*)(lds + (bufoff) + ldsw + _i * 8192), 16, 0, 0); } while (0)
; #define LDA(dst, b, h) do { _Pragma("unroll") for (int m = 0; m < 4; ++m) _Pragma("unroll") for (int k = 0; k < 2; ++k) dst[m][k] = *(const LAS half8*)(lds + SA(b, h) + aoff + m * 2048 + k * 1024); } while (0)
; #define LDB(dst, b, h) do { _Pragma("unroll") for (int n = 0; n < 2; ++n) _Pragma("unroll") for (int k = 0; k < 2; ++k) dst[n][k] = *(const LAS half8*)(lds + SB(b, h) + boff + n * 2048 + k * 1024); } while (0)
; #define MMA(ai, bj, At_, Bt_) do { __builtin_amdgcn_s_setprio(1); \
;     _Pragma("unroll") for (int m = 0; m < 4; ++m) _Pragma("unroll") for (int n = 0; n < 2; ++n) _Pragma("unroll") for (int k = 0; k < 2; ++k) \
;       acc[ai][bj][m][n] = MFMA16(Bt_[n][k], At_[m][k], acc[ai][bj][m][n]); \
;     __builtin_amdgcn_s_setprio(0); } while (0)
; #define WAIT_V(n) asm volatile("s_waitcnt vmcnt(" #n ")" ::: "memory")
; #define WAIT_L(n) asm volatile("s_waitcnt lgkmcnt(" #n ")" ::: "memory")
; #define BAR __builtin_amdgcn_s_barrier()
; #define SCHED __builtin_amdgcn_sched_barrier(0)
; template <int EPI>
; DI void gemm_phase(const int wid_s, const h16* __restrict__ A, const h16* __restrict__ Bt, const int N, const int K, const EpiArgs ea) {
;     ...
;       const char* a1 = cA + (size_t)(t + 1) * kstep;
;       const char* a2 = last ? nA : cA + (size_t)(t + 2) * kstep; const char* b2 = last ? nB : cB + (size_t)(t + 2) * kstep;
;       const char* a3 = a2 + kstep; const char* b3 = b2 + kstep;
;       LDB(B0, 0, 0); LDB(B1, 0, 1); SCHED; LDA(At, 0, 0); STAGE(SA(1, 1), a1 + hstep, voffA);
;       WAIT_V(8); WAIT_L(0); BAR; MMA(0, 0, At, B0); MMA(0, 1, At, B1); BAR; SCHED;
;       LDA(At, 0, 1); STAGE(SB(0, 0), b2, voffB); STAGE(SB(0, 1), b2 + hstep, voffB); STAGE(SA(0, 0), a2, voffA);
;       WAIT_V(8); WAIT_L(0); BAR; MMA(1, 0, At, B0); MMA(1, 1, At, B1); BAR; SCHED;
.LBB0_386:
	s_add_u32 s22, s45, s20
	s_addc_u32 s23, s46, s21
	s_add_u32 s22, s22, 0x520e100
	s_addc_u32 s23, s23, 0
	s_add_u32 s48, s43, s20
	s_addc_u32 s49, s44, s21
	s_add_i32 s50, 0, 0x10000
	s_cmpk_eq_i32 s20, 0x700
	s_cselect_b32 s27, s41, s23
	s_cselect_b32 s26, s9, s22
	v_add_u32_e32 v177, s50, v148
	s_cselect_b32 s23, s42, s49
	s_cselect_b32 s22, s11, s48
	s_add_i32 s51, 0, 0x14000
	ds_read_b128 v[152:155], v177
	ds_read_b128 v[178:181], v177 offset:1024
	ds_read_b128 v[182:185], v177 offset:2048
	ds_read_b128 v[186:189], v177 offset:3072
	v_add_u32_e32 v177, s51, v148
	ds_read_b128 v[190:193], v177
	ds_read_b128 v[194:197], v177 offset:1024
	ds_read_b128 v[198:201], v177 offset:2048
	ds_read_b128 v[202:205], v177 offset:3072
	v_lshl_add_u64 v[238:239], v[146:147], 0, s[20:21]
	s_add_i32 m0, s13, 0xc000
	ds_read_b128 v[206:209], v151
	ds_read_b128 v[210:213], v151 offset:1024
	ds_read_b128 v[214:217], v151 offset:2048
	ds_read_b128 v[218:221], v151 offset:3072
	ds_read_b128 v[222:225], v151 offset:4096
	ds_read_b128 v[226:229], v151 offset:5120
	ds_read_b128 v[230:233], v151 offset:6144
	ds_read_b128 v[234:237], v151 offset:7168
	global_load_lds_dwordx4 v[238:239], off
	v_lshl_add_u64 v[238:239], v[144:145], 0, s[20:21]
	s_add_i32 m0, s13, 0xe000
	s_nop 0
	global_load_lds_dwordx4 v[238:239], off
	s_waitcnt vmcnt(8)
	s_waitcnt lgkmcnt(0)
	s_barrier
	s_waitcnt lgkmcnt(0)
	v_mfma_f32_16x16x32_f16 v[130:133], v[152:155], v[206:209], v[130:133]
	v_mfma_f32_16x16x32_f16 v[126:129], v[182:185], v[206:209], v[126:129]
	v_mfma_f32_16x16x32_f16 v[122:125], v[152:155], v[214:217], v[122:125]
	v_mfma_f32_16x16x32_f16 v[118:121], v[182:185], v[214:217], v[118:121]
	v_mfma_f32_16x16x32_f16 v[106:109], v[152:155], v[222:225], v[106:109]
	v_mfma_f32_16x16x32_f16 v[102:105], v[182:185], v[222:225], v[102:105]
	v_mfma_f32_16x16x32_f16 v[90:93], v[152:155], v[230:233], v[90:93]
	v_mfma_f32_16x16x32_f16 v[86:89], v[182:185], v[230:233], v[86:89]
	v_mfma_f32_16x16x32_f16 v[130:133], v[178:181], v[210:213], v[130:133]
	v_mfma_f32_16x16x32_f16 v[126:129], v[186:189], v[210:213], v[126:129]
	v_mfma_f32_16x16x32_f16 v[122:125], v[178:181], v[218:221], v[122:125]
	v_mfma_f32_16x16x32_f16 v[118:121], v[186:189], v[218:221], v[118:121]
	v_mfma_f32_16x16x32_f16 v[106:109], v[178:181], v[226:229], v[106:109]
	v_mfma_f32_16x16x32_f16 v[102:105], v[186:189], v[226:229], v[102:105]
	v_mfma_f32_16x16x32_f16 v[90:93], v[178:181], v[234:237], v[90:93]
	v_mfma_f32_16x16x32_f16 v[86:89], v[186:189], v[234:237], v[86:89]
	v_mfma_f32_16x16x32_f16 v[114:117], v[190:193], v[206:209], v[114:117]
	v_mfma_f32_16x16x32_f16 v[110:113], v[198:201], v[206:209], v[110:113]
	v_mfma_f32_16x16x32_f16 v[98:101], v[190:193], v[214:217], v[98:101]
	v_mfma_f32_16x16x32_f16 v[94:97], v[198:201], v[214:217], v[94:97]
	v_mfma_f32_16x16x32_f16 v[82:85], v[190:193], v[222:225], v[82:85]
	v_mfma_f32_16x16x32_f16 v[78:81], v[198:201], v[222:225], v[78:81]
	v_mfma_f32_16x16x32_f16 v[74:77], v[190:193], v[230:233], v[74:77]
	v_mfma_f32_16x16x32_f16 v[70:73], v[198:201], v[230:233], v[70:73]
	v_mfma_f32_16x16x32_f16 v[114:117], v[194:197], v[210:213], v[114:117]
	v_mfma_f32_16x16x32_f16 v[110:113], v[202:205], v[210:213], v[110:113]
	v_mfma_f32_16x16x32_f16 v[98:101], v[194:197], v[218:221], v[98:101]
	v_mfma_f32_16x16x32_f16 v[94:97], v[202:205], v[218:221], v[94:97]
	v_mfma_f32_16x16x32_f16 v[82:85], v[194:197], v[226:229], v[82:85]
	v_mfma_f32_16x16x32_f16 v[78:81], v[202:205], v[226:229], v[78:81]
	v_mfma_f32_16x16x32_f16 v[74:77], v[194:197], v[234:237], v[74:77]
	v_mfma_f32_16x16x32_f16 v[70:73], v[202:205], v[234:237], v[70:73]
	s_barrier
	s_add_i32 s48, s50, s30
	v_lshl_add_u64 v[238:239], s[22:23], 0, v[0:1]
	s_mov_b32 m0, s48
	ds_read_b128 v[206:209], v151 offset:16384
	ds_read_b128 v[210:213], v151 offset:17408
	ds_read_b128 v[214:217], v151 offset:18432
	ds_read_b128 v[218:221], v151 offset:19456
	ds_read_b128 v[222:225], v151 offset:20480
	ds_read_b128 v[226:229], v151 offset:21504
	ds_read_b128 v[230:233], v151 offset:22528
	ds_read_b128 v[234:237], v151 offset:23552
	global_load_lds_dwordx4 v[238:239], off
	s_add_i32 m0, s48, 0x2000
	s_add_u32 s48, s22, 0x40000
	v_lshl_add_u64 v[240:241], s[22:23], 0, v[2:3]
	s_addc_u32 s49, s23, 0
	s_add_i32 s50, s51, s30
	global_load_lds_dwordx4 v[240:241], off
	v_lshl_add_u64 v[242:243], s[48:49], 0, v[0:1]
	s_mov_b32 m0, s50
	v_lshl_add_u64 v[244:245], s[26:27], 0, v[134:135]
	global_load_lds_dwordx4 v[242:243], off
	v_lshl_add_u64 v[242:243], s[48:49], 0, v[2:3]
	s_add_i32 m0, s50, 0x2000
	s_nop 0
	global_load_lds_dwordx4 v[242:243], off
	v_lshl_add_u64 v[242:243], s[26:27], 0, v[138:139]
	s_mov_b32 m0, s13
	s_nop 0
	global_load_lds_dwordx4 v[242:243], off
	s_mov_b32 m0, s15
	s_nop 0
	global_load_lds_dwordx4 v[244:245], off
	s_waitcnt vmcnt(8)
	s_waitcnt lgkmcnt(0)
	s_barrier
; #define STAGE(bufoff, gbase, voff) do { _Pragma("unroll") for (int _i = 0; _i < 2; ++_i) \
;     __builtin_amdgcn_global_load_lds((const unsigned*)((const char*)(gbase) + (voff)[_i]), (LAS unsigned*)(lds + (bufoff) + ldsw + _i * 8192), 16, 0, 0); } while (0)
; #define LDA(dst, b, h) do { _Pragma("unroll") for (int m = 0; m < 4; ++m) _Pragma("unroll") for (int k = 0; k < 2; ++k) dst[m][k] = *(const LAS half8*)(lds + SA(b, h) + aoff + m * 2048 + k * 1024); } while (0)
; #define LDB(dst, b, h) do { _Pragma("unroll") for (int n = 0; n < 2; ++n) _Pragma("unroll") for (int k = 0; k < 2; ++k) dst[n][k] = *(const LAS half8*)(lds + SB(b, h) + boff + n * 2048 + k * 1024); } while (0)
; #define MMA(ai, bj, At_, Bt_) do { __builtin_amdgcn_s_setprio(1); \
;     _Pragma("unroll") for (int m = 0; m < 4; ++m) _Pragma("unroll") for (int n = 0; n < 2; ++n) _Pragma("unroll") for (int k = 0; k < 2; ++k) \
;       acc[ai][bj][m][n] = MFMA16(Bt_[n][k], At_[m][k], acc[ai][bj][m][n]); \
;     __builtin_amdgcn_s_setprio(0); } while (0)
; #define WAIT_V(n) asm volatile("s_waitcnt vmcnt(" #n ")" ::: "memory")
; #define WAIT_L(n) asm volatile("s_waitcnt lgkmcnt(" #n ")" ::: "memory")
; #define BAR __builtin_amdgcn_s_barrier()
; #define SCHED __builtin_amdgcn_sched_barrier(0)
; template <int EPI>
; DI void gemm_phase(const int wid_s, const h16* __restrict__ A, const h16* __restrict__ Bt, const int N, const int K, const EpiArgs ea) {
;     ...
;       WAIT_V(8); WAIT_L(0); BAR; MMA(1, 0, At, B0); MMA(1, 1, At, B1); BAR; SCHED;
;       LDB(B0, 1, 0); LDB(B1, 1, 1); SCHED; LDA(At, 1, 0); STAGE(SA(0, 1), a2 + hstep, voffA);
;       WAIT_V(8); WAIT_L(0); BAR; MMA(0, 0, At, B0); MMA(0, 1, At, B1); BAR; SCHED;
	s_waitcnt lgkmcnt(0)
	v_mfma_f32_16x16x32_f16 v[66:69], v[152:155], v[206:209], v[66:69]
	v_mfma_f32_16x16x32_f16 v[62:65], v[182:185], v[206:209], v[62:65]
	v_mfma_f32_16x16x32_f16 v[58:61], v[152:155], v[214:217], v[58:61]
	v_mfma_f32_16x16x32_f16 v[54:57], v[182:185], v[214:217], v[54:57]
	v_mfma_f32_16x16x32_f16 v[42:45], v[152:155], v[222:225], v[42:45]
	v_mfma_f32_16x16x32_f16 v[38:41], v[182:185], v[222:225], v[38:41]
	v_mfma_f32_16x16x32_f16 v[26:29], v[152:155], v[230:233], v[26:29]
	v_mfma_f32_16x16x32_f16 v[22:25], v[182:185], v[230:233], v[22:25]
	v_mfma_f32_16x16x32_f16 v[66:69], v[178:181], v[210:213], v[66:69]
	v_mfma_f32_16x16x32_f16 v[62:65], v[186:189], v[210:213], v[62:65]
	v_mfma_f32_16x16x32_f16 v[58:61], v[178:181], v[218:221], v[58:61]
	v_mfma_f32_16x16x32_f16 v[54:57], v[186:189], v[218:221], v[54:57]
	v_mfma_f32_16x16x32_f16 v[42:45], v[178:181], v[226:229], v[42:45]
	v_mfma_f32_16x16x32_f16 v[38:41], v[186:189], v[226:229], v[38:41]
	v_mfma_f32_16x16x32_f16 v[26:29], v[178:181], v[234:237], v[26:29]
	v_mfma_f32_16x16x32_f16 v[22:25], v[186:189], v[234:237], v[22:25]
	v_mfma_f32_16x16x32_f16 v[50:53], v[190:193], v[206:209], v[50:53]
	v_mfma_f32_16x16x32_f16 v[46:49], v[198:201], v[206:209], v[46:49]
	v_mfma_f32_16x16x32_f16 v[34:37], v[190:193], v[214:217], v[34:37]
	v_mfma_f32_16x16x32_f16 v[30:33], v[198:201], v[214:217], v[30:33]
	v_mfma_f32_16x16x32_f16 v[18:21], v[190:193], v[222:225], v[18:21]
	v_mfma_f32_16x16x32_f16 v[14:17], v[198:201], v[222:225], v[14:17]
	v_mfma_f32_16x16x32_f16 v[10:13], v[190:193], v[230:233], v[10:13]
	v_mfma_f32_16x16x32_f16 v[6:9], v[198:201], v[230:233], v[6:9]
	v_mfma_f32_16x16x32_f16 v[50:53], v[194:197], v[210:213], v[50:53]
	v_mfma_f32_16x16x32_f16 v[46:49], v[202:205], v[210:213], v[46:49]
	v_mfma_f32_16x16x32_f16 v[34:37], v[194:197], v[218:221], v[34:37]
	v_mfma_f32_16x16x32_f16 v[30:33], v[202:205], v[218:221], v[30:33]
	v_mfma_f32_16x16x32_f16 v[18:21], v[194:197], v[226:229], v[18:21]
	v_mfma_f32_16x16x32_f16 v[14:17], v[202:205], v[226:229], v[14:17]
	v_mfma_f32_16x16x32_f16 v[10:13], v[194:197], v[234:237], v[10:13]
	v_mfma_f32_16x16x32_f16 v[6:9], v[202:205], v[234:237], v[6:9]
	s_barrier
	s_add_i32 s48, 0, 0x18000
	v_add_u32_e32 v177, s48, v148
	s_add_i32 s49, 0, 0x1c000
	ds_read_b128 v[152:155], v177
	ds_read_b128 v[178:181], v177 offset:1024
	ds_read_b128 v[182:185], v177 offset:2048
	ds_read_b128 v[186:189], v177 offset:3072
	v_add_u32_e32 v177, s49, v148
	ds_read_b128 v[190:193], v177
	ds_read_b128 v[194:197], v177 offset:1024
	ds_read_b128 v[198:201], v177 offset:2048
	ds_read_b128 v[202:205], v177 offset:3072
	s_add_u32 s26, s26, 0x40000
	s_addc_u32 s27, s27, 0
	s_mov_b32 m0, s31
	v_lshl_add_u64 v[246:247], s[26:27], 0, v[138:139]
	ds_read_b128 v[206:209], v151 offset:32768
	ds_read_b128 v[210:213], v151 offset:33792
	ds_read_b128 v[214:217], v151 offset:34816
	ds_read_b128 v[218:221], v151 offset:35840
	ds_read_b128 v[222:225], v151 offset:36864
	ds_read_b128 v[226:229], v151 offset:37888
	ds_read_b128 v[230:233], v151 offset:38912
	ds_read_b128 v[234:237], v151 offset:39936
	global_load_lds_dwordx4 v[246:247], off
	v_lshl_add_u64 v[246:247], s[26:27], 0, v[134:135]
	s_mov_b32 m0, s38
	s_nop 0
	global_load_lds_dwordx4 v[246:247], off
	s_waitcnt vmcnt(8)
	s_waitcnt lgkmcnt(0)
	s_barrier
	s_waitcnt lgkmcnt(0)
	v_mfma_f32_16x16x32_f16 v[130:133], v[152:155], v[206:209], v[130:133]
	v_mfma_f32_16x16x32_f16 v[126:129], v[182:185], v[206:209], v[126:129]
	v_mfma_f32_16x16x32_f16 v[122:125], v[152:155], v[214:217], v[122:125]
	v_mfma_f32_16x16x32_f16 v[118:121], v[182:185], v[214:217], v[118:121]
	v_mfma_f32_16x16x32_f16 v[106:109], v[152:155], v[222:225], v[106:109]
	v_mfma_f32_16x16x32_f16 v[102:105], v[182:185], v[222:225], v[102:105]
	v_mfma_f32_16x16x32_f16 v[90:93], v[152:155], v[230:233], v[90:93]
	v_mfma_f32_16x16x32_f16 v[86:89], v[182:185], v[230:233], v[86:89]
	v_mfma_f32_16x16x32_f16 v[130:133], v[178:181], v[210:213], v[130:133]
	v_mfma_f32_16x16x32_f16 v[126:129], v[186:189], v[210:213], v[126:129]
	v_mfma_f32_16x16x32_f16 v[122:125], v[178:181], v[218:221], v[122:125]
	v_mfma_f32_16x16x32_f16 v[118:121], v[186:189], v[218:221], v[118:121]
	v_mfma_f32_16x16x32_f16 v[106:109], v[178:181], v[226:229], v[106:109]
	v_mfma_f32_16x16x32_f16 v[102:105], v[186:189], v[226:229], v[102:105]
	v_mfma_f32_16x16x32_f16 v[90:93], v[178:181], v[234:237], v[90:93]
	v_mfma_f32_16x16x32_f16 v[86:89], v[186:189], v[234:237], v[86:89]
	v_mfma_f32_16x16x32_f16 v[114:117], v[190:193], v[206:209], v[114:117]
	v_mfma_f32_16x16x32_f16 v[110:113], v[198:201], v[206:209], v[110:113]
	v_mfma_f32_16x16x32_f16 v[98:101], v[190:193], v[214:217], v[98:101]
	v_mfma_f32_16x16x32_f16 v[94:97], v[198:201], v[214:217], v[94:97]
	v_mfma_f32_16x16x32_f16 v[82:85], v[190:193], v[222:225], v[82:85]
	v_mfma_f32_16x16x32_f16 v[78:81], v[198:201], v[222:225], v[78:81]
	v_mfma_f32_16x16x32_f16 v[74:77], v[190:193], v[230:233], v[74:77]
	v_mfma_f32_16x16x32_f16 v[70:73], v[198:201], v[230:233], v[70:73]
	v_mfma_f32_16x16x32_f16 v[114:117], v[194:197], v[210:213], v[114:117]
	v_mfma_f32_16x16x32_f16 v[110:113], v[202:205], v[210:213], v[110:113]
	v_mfma_f32_16x16x32_f16 v[98:101], v[194:197], v[218:221], v[98:101]
	v_mfma_f32_16x16x32_f16 v[94:97], v[202:205], v[218:221], v[94:97]
	v_mfma_f32_16x16x32_f16 v[82:85], v[194:197], v[226:229], v[82:85]
	v_mfma_f32_16x16x32_f16 v[78:81], v[202:205], v[226:229], v[78:81]
	v_mfma_f32_16x16x32_f16 v[74:77], v[194:197], v[234:237], v[74:77]
	v_mfma_f32_16x16x32_f16 v[70:73], v[202:205], v[234:237], v[70:73]
	s_barrier
; #define STAGE(bufoff, gbase, voff) do { _Pragma("unroll") for (int _i = 0; _i < 2; ++_i) \
;     __builtin_amdgcn_global_load_lds((const unsigned*)((const char*)(gbase) + (voff)[_i]), (LAS unsigned*)(lds + (bufoff) + ldsw + _i * 8192), 16, 0, 0); } while (0)
; #define LDA(dst, b, h) do { _Pragma("unroll") for (int m = 0; m < 4; ++m) _Pragma("unroll") for (int k = 0; k < 2; ++k) dst[m][k] = *(const LAS half8*)(lds + SA(b, h) + aoff + m * 2048 + k * 1024); } while (0)
; #define MMA(ai, bj, At_, Bt_) do { __builtin_amdgcn_s_setprio(1); \
;     _Pragma("unroll") for (int m = 0; m < 4; ++m) _Pragma("unroll") for (int n = 0; n < 2; ++n) _Pragma("unroll") for (int k = 0; k < 2; ++k) \
;       acc[ai][bj][m][n] = MFMA16(Bt_[n][k], At_[m][k], acc[ai][bj][m][n]); \
;     __builtin_amdgcn_s_setprio(0); } while (0)
; #define WAIT_V(n) asm volatile("s_waitcnt vmcnt(" #n ")" ::: "memory")
; #define WAIT_L(n) asm volatile("s_waitcnt lgkmcnt(" #n ")" ::: "memory")
; #define BAR __builtin_amdgcn_s_barrier()
; #define SCHED __builtin_amdgcn_sched_barrier(0)
; template <int EPI>
; DI void gemm_phase(const int wid_s, const h16* __restrict__ A, const h16* __restrict__ Bt, const int N, const int K, const EpiArgs ea) {
;     ...
;     for (int t = 0; t < nt; t += 2) {
;     ...
;       LDA(At, 1, 1); STAGE(SB(1, 0), b3, voffB); STAGE(SB(1, 1), b3 + hstep, voffB); STAGE(SA(1, 0), a3, voffA);
;       WAIT_V(8); WAIT_L(0); BAR; MMA(1, 0, At, B0); MMA(1, 1, At, B1); BAR; SCHED;
;     }
	s_add_i32 s26, s48, s30
	v_lshl_add_u64 v[238:239], v[238:239], 0, s[36:37]
	s_mov_b32 m0, s26
	ds_read_b128 v[206:209], v151 offset:49152
	ds_read_b128 v[210:213], v151 offset:50176
	ds_read_b128 v[214:217], v151 offset:51200
	ds_read_b128 v[218:221], v151 offset:52224
	ds_read_b128 v[222:225], v151 offset:53248
	ds_read_b128 v[226:229], v151 offset:54272
	ds_read_b128 v[230:233], v151 offset:55296
	ds_read_b128 v[234:237], v151 offset:56320
	global_load_lds_dwordx4 v[238:239], off
	s_add_i32 m0, s26, 0x2000
	s_add_u32 s22, s22, 0x40080
	v_lshl_add_u64 v[238:239], v[240:241], 0, s[36:37]
	s_addc_u32 s23, s23, 0
	s_add_i32 s26, s49, s30
	global_load_lds_dwordx4 v[238:239], off
	v_lshl_add_u64 v[238:239], s[22:23], 0, v[0:1]
	s_mov_b32 m0, s26
	s_nop 0
	global_load_lds_dwordx4 v[238:239], off
	v_lshl_add_u64 v[238:239], s[22:23], 0, v[2:3]
	s_add_i32 m0, s26, 0x2000
	s_nop 0
	global_load_lds_dwordx4 v[238:239], off
	v_lshl_add_u64 v[238:239], v[242:243], 0, s[36:37]
	s_mov_b32 m0, s39
	s_nop 0
	global_load_lds_dwordx4 v[238:239], off
	v_lshl_add_u64 v[238:239], v[244:245], 0, s[36:37]
	s_mov_b32 m0, s40
	s_nop 0
	global_load_lds_dwordx4 v[238:239], off
	s_waitcnt vmcnt(8)
	s_waitcnt lgkmcnt(0)
	s_barrier
	s_waitcnt lgkmcnt(0)
	v_mfma_f32_16x16x32_f16 v[66:69], v[152:155], v[206:209], v[66:69]
	v_mfma_f32_16x16x32_f16 v[62:65], v[182:185], v[206:209], v[62:65]
	v_mfma_f32_16x16x32_f16 v[58:61], v[152:155], v[214:217], v[58:61]
	v_mfma_f32_16x16x32_f16 v[54:57], v[182:185], v[214:217], v[54:57]
	v_mfma_f32_16x16x32_f16 v[42:45], v[152:155], v[222:225], v[42:45]
	v_mfma_f32_16x16x32_f16 v[38:41], v[182:185], v[222:225], v[38:41]
	v_mfma_f32_16x16x32_f16 v[26:29], v[152:155], v[230:233], v[26:29]
	v_mfma_f32_16x16x32_f16 v[22:25], v[182:185], v[230:233], v[22:25]
	v_mfma_f32_16x16x32_f16 v[66:69], v[178:181], v[210:213], v[66:69]
	v_mfma_f32_16x16x32_f16 v[62:65], v[186:189], v[210:213], v[62:65]
	v_mfma_f32_16x16x32_f16 v[58:61], v[178:181], v[218:221], v[58:61]
	v_mfma_f32_16x16x32_f16 v[54:57], v[186:189], v[218:221], v[54:57]
	v_mfma_f32_16x16x32_f16 v[42:45], v[178:181], v[226:229], v[42:45]
	v_mfma_f32_16x16x32_f16 v[38:41], v[186:189], v[226:229], v[38:41]
	v_mfma_f32_16x16x32_f16 v[26:29], v[178:181], v[234:237], v[26:29]
	v_mfma_f32_16x16x32_f16 v[22:25], v[186:189], v[234:237], v[22:25]
	v_mfma_f32_16x16x32_f16 v[50:53], v[190:193], v[206:209], v[50:53]
	v_mfma_f32_16x16x32_f16 v[46:49], v[198:201], v[206:209], v[46:49]
	v_mfma_f32_16x16x32_f16 v[34:37], v[190:193], v[214:217], v[34:37]
	v_mfma_f32_16x16x32_f16 v[30:33], v[198:201], v[214:217], v[30:33]
	v_mfma_f32_16x16x32_f16 v[18:21], v[190:193], v[222:225], v[18:21]
	v_mfma_f32_16x16x32_f16 v[14:17], v[198:201], v[222:225], v[14:17]
	v_mfma_f32_16x16x32_f16 v[10:13], v[190:193], v[230:233], v[10:13]
	v_mfma_f32_16x16x32_f16 v[6:9], v[198:201], v[230:233], v[6:9]
	v_mfma_f32_16x16x32_f16 v[50:53], v[194:197], v[210:213], v[50:53]
	v_mfma_f32_16x16x32_f16 v[46:49], v[202:205], v[210:213], v[46:49]
	v_mfma_f32_16x16x32_f16 v[34:37], v[194:197], v[218:221], v[34:37]
	v_mfma_f32_16x16x32_f16 v[30:33], v[202:205], v[218:221], v[30:33]
	v_mfma_f32_16x16x32_f16 v[18:21], v[194:197], v[226:229], v[18:21]
	v_mfma_f32_16x16x32_f16 v[14:17], v[202:205], v[226:229], v[14:17]
	v_mfma_f32_16x16x32_f16 v[10:13], v[194:197], v[234:237], v[10:13]
	v_mfma_f32_16x16x32_f16 v[6:9], v[202:205], v[234:237], v[6:9]
	s_barrier
	s_add_i32 s47, s47, 2
	s_add_u32 s20, s20, 0x100
	s_addc_u32 s21, s21, 0
	s_cmp_gt_u32 s47, 13
	s_cbranch_scc0 .LBB0_386
	s_and_b64 vcc, exec, s[4:5]
	s_cbranch_vccz .LBB0_389
	s_barrier
